# v52 plus the peeled first load section's fragment reads issued at the start of the unit header (LDS latency under the next-unit index arithmetic)
# baseline (speedup 1.0000x reference)
;     __device__ __forceinline__ size_t aoff(const Unit& u) const { return (size_t)u.pm * bm * lda * 2; }
;     __device__ __forceinline__ size_t boff(const Unit& u) const { return (size_t)u.pn * BM * ldb * 2; }
;     __device__ __forceinline__ size_t aoff(const Unit& u) const { return ((size_t)u.pm * BM * lda + (size_t)u.pn * akoff) * 2; }
;     __device__ __forceinline__ size_t boff(const Unit& u) const { return (size_t)u.pn * BM * ldb * 2; }
;     __device__ __forceinline__ size_t aoff(const Unit& u) const { return ((size_t)u.pm * BM * lda + (size_t)(u.pn >> 1) * akoff) * 2; }
;     __device__ __forceinline__ size_t boff(const Unit& u) const { return (size_t)u.pn * BM * ldb * 2; }
; #define PG8_STAGE(bufoff, gbase, voff) do { _Pragma("unroll") for (int _i = 0; _i < 2; ++_i) \
;         __builtin_amdgcn_global_load_lds((const unsigned*)((const char*)(gbase) + (voff)[_i]), (LAS unsigned*)(lds + (bufoff) + ldsw + _i * 8192), 16, 0, 0); } while (0)
; #define PG8_SCHED __builtin_amdgcn_sched_barrier(0)
;     __device__ bool next(int i, Unit& u) const {
;         const long L = (long)i * G + c; if (L >= nwg) return false;
;         int wgid = (int)L; { const int q = nwg / NXCD, r = nwg % NXCD, xcd = wgid % NXCD, off = wgid / NXCD; wgid = (xcd < r ? xcd * (q + 1) : r * (q + 1) + (xcd - r) * q) + off; }
;         const int nig = WGM * nN, gid = wgid / nig, fm = gid * WGM, gsz = (nM - fm) < WGM ? (nM - fm) : WGM;
;         u.pm = fm + ((wgid % nig) % gsz); u.pn = (wgid % nig) / gsz; return true;
;     }
;     ...
;         const bool has_next = S.next(ui + 1, nxt);
;         const char* nA = has_next ? (const char*)g.A + S.aoff(nxt) : cA; const char* nB = has_next ? (const char*)g.Bt + S.boff(nxt) : cB;
;         if constexpr (Epi::PRE) E.pre(lds, cur, wid);
;         for (int t = 0; t < nt; t += 2) {
;             const bool last = (t == nt - 2);
;             const char* a1 = cA + (size_t)(t + 1) * kstep;
;             const char* a2 = last ? nA : cA + (size_t)(t + 2) * kstep; const char* b2 = last ? nB : cB + (size_t)(t + 2) * kstep;
;             const char* a3 = a2 + kstep; const char* b3 = b2 + kstep;
;             if constexpr (SP2) {
;             PG8_LDB(B0, 0, 0); PG8_LDB(B1, 0, 1); PG8_SCHED; PG8_LDA(At, 0, 0); PG8_STAGE(PG8_SA(1, 1), a1 + hstepA, voffA);
.LBB0_195:
	ds_read_b128 v[26:29], v172
	ds_read_b128 v[30:33], v172 offset:1024
	ds_read_b128 v[42:45], v172 offset:2048
	ds_read_b128 v[46:49], v172 offset:3072
	ds_read_b128 v[146:149], v173
	ds_read_b128 v[150:153], v173 offset:1024
	ds_read_b128 v[164:167], v173 offset:2048
	ds_read_b128 v[168:171], v173 offset:3072
	ds_read_b128 v[178:181], v174
	ds_read_b128 v[182:185], v174 offset:1024
	ds_read_b128 v[186:189], v174 offset:2048
	ds_read_b128 v[190:193], v174 offset:3072
	ds_read_b128 v[194:197], v174 offset:4096
	ds_read_b128 v[198:201], v174 offset:5120
	ds_read_b128 v[202:205], v174 offset:6144
	ds_read_b128 v[206:209], v174 offset:7168
	s_add_i32 s70, s70, 1
	s_mul_i32 s2, s70, s62
	s_mul_hi_u32 s3, s70, s53
	s_add_i32 s3, s3, s2
	s_mul_i32 s2, s70, s53
	v_readlane_b32 s4, v255, 29
	s_add_u32 s2, s2, s4
	s_addc_u32 s3, s3, s63
	v_mov_b64_e32 v[2:3], 0x900
	v_cmp_lt_i64_e64 s[4:5], s[2:3], v[2:3]
	v_mov_b64_e32 v[2:3], 0x8ff
	v_cmp_gt_i64_e32 vcc, s[2:3], v[2:3]
	s_nop 3
	s_mov_b32 s101, s4
	s_cbranch_vccnz .LBB0_197
	s_ashr_i32 s3, s2, 31
	s_lshr_b32 s3, s3, 29
	s_add_i32 s3, s2, s3
	s_ashr_i32 s9, s3, 3
	s_and_b32 s3, s3, -8
	s_sub_i32 s2, s2, s3
	s_cmp_lt_i32 s2, 0
	s_cselect_b32 s3, s95, 0x120
	s_mul_i32 s2, s2, s3
	s_add_i32 s2, s2, s9
	s_ashr_i32 s3, s2, 31
	s_lshr_b32 s3, s3, 24
	s_add_i32 s3, s2, s3
	s_ashr_i32 s9, s3, 8
	s_lshl_b32 s9, s9, 3
	s_sub_i32 s20, 0x48, s9
	s_min_i32 s21, s20, 8
	s_abs_i32 s20, s21
	v_cvt_f32_u32_e32 v2, s20
	s_sub_i32 s23, 0, s20
	s_and_b32 s3, s3, 0xffffff00
	s_sub_i32 s2, s2, s3
	v_rcp_iflag_f32_e32 v2, v2
	s_abs_i32 s3, s2
	s_xor_b32 s22, s2, s21
	s_ashr_i32 s22, s22, 31
	v_mul_f32_e32 v2, 0x4f7ffffe, v2
	v_cvt_u32_f32_e32 v2, v2
	s_nop 0
	v_readfirstlane_b32 s24, v2
	s_mul_i32 s23, s23, s24
	s_mul_hi_u32 s23, s24, s23
	s_add_i32 s24, s24, s23
	s_mul_hi_u32 s23, s3, s24
	s_mul_i32 s24, s23, s20
	s_sub_i32 s3, s3, s24
	s_add_i32 s25, s23, 1
	s_sub_i32 s24, s3, s20
	s_cmp_ge_u32 s3, s20
	s_cselect_b32 s23, s25, s23
	s_cselect_b32 s3, s24, s3
	s_add_i32 s24, s23, 1
	s_cmp_ge_u32 s3, s20
	s_cselect_b32 s3, s24, s23
	s_xor_b32 s3, s3, s22
	s_sub_i32 s20, s3, s22
	s_mul_i32 s3, s20, s21
	s_sub_i32 s2, s2, s3
	s_add_i32 s22, s9, s2

;     __device__ __forceinline__ size_t aoff(const Unit& u) const { return (size_t)u.pm * bm * lda * 2; }
;     __device__ __forceinline__ size_t boff(const Unit& u) const { return (size_t)u.pn * BM * ldb * 2; }
;     __device__ __forceinline__ size_t aoff(const Unit& u) const { return ((size_t)u.pm * BM * lda + (size_t)u.pn * akoff) * 2; }
;     __device__ __forceinline__ size_t boff(const Unit& u) const { return (size_t)u.pn * BM * ldb * 2; }
;     __device__ __forceinline__ size_t aoff(const Unit& u) const { return ((size_t)u.pm * BM * lda + (size_t)(u.pn >> 1) * akoff) * 2; }
;     __device__ __forceinline__ size_t boff(const Unit& u) const { return (size_t)u.pn * BM * ldb * 2; }
; #define PG8_STAGE(bufoff, gbase, voff) do { _Pragma("unroll") for (int _i = 0; _i < 2; ++_i) \
;         __builtin_amdgcn_global_load_lds((const unsigned*)((const char*)(gbase) + (voff)[_i]), (LAS unsigned*)(lds + (bufoff) + ldsw + _i * 8192), 16, 0, 0); } while (0)
; #define PG8_LDA(dst, b, h) do { _Pragma("unroll") for (int m = 0; m < NM; ++m) _Pragma("unroll") for (int k = 0; k < 2; ++k) dst[m][k] = *(const LAS bf16x8*)(lds + PG8_SA(b, h) + aoff + m * 2048 + k * 1024); } while (0)
; #define PG8_BAR __builtin_amdgcn_s_barrier()
;     ...
;         const bool has_next = S.next(ui + 1, nxt);
;         const char* nA = has_next ? (const char*)g.A + S.aoff(nxt) : cA; const char* nB = has_next ? (const char*)g.Bt + S.boff(nxt) : cB;
;         if constexpr (Epi::PRE) E.pre(lds, cur, wid);
;         for (int t = 0; t < nt; t += 2) {
;             const bool last = (t == nt - 2);
;             const char* a1 = cA + (size_t)(t + 1) * kstep;
;             const char* a2 = last ? nA : cA + (size_t)(t + 2) * kstep; const char* b2 = last ? nB : cB + (size_t)(t + 2) * kstep;
;             const char* a3 = a2 + kstep; const char* b3 = b2 + kstep;
;             if constexpr (SP2) {
;             PG8_LDB(B0, 0, 0); PG8_LDB(B1, 0, 1); PG8_SCHED; PG8_LDA(At, 0, 0); PG8_STAGE(PG8_SA(1, 1), a1 + hstepA, voffA);
;             PG8_WAIT_V(8); PG8_WAIT_L(0); PG8_BAR; PG8_MMA(0, 0, At, B0); PG8_MMA(0, 1, At, B1); PG8_BAR; PG8_SCHED;
;             PG8_LDA(At, 0, 1); PG8_STAGE(PG8_SB(0, 0), b2, voffB); PG8_STAGE(PG8_SB(0, 1), b2 + hstepB, voffB); PG8_STAGE(PG8_SA(0, 0), a2, voffA);
;             PG8_WAIT_V(8); PG8_WAIT_L(0); PG8_BAR; PG8_MMA(1, 0, At, B0); PG8_MMA(1, 1, At, B1); PG8_BAR; PG8_SCHED;
.LBB0_199:
	s_ashr_i32 s23, s22, 31
	s_lshl_b64 s[2:3], s[22:23], 20
	s_add_u32 s24, s33, s2
	s_addc_u32 s25, s36, s3
	s_and_b64 s[2:3], s[4:5], exec
	s_cselect_b32 s2, s25, s29
	s_cselect_b32 s3, s24, s28
	s_ashr_i32 s21, s20, 31
	s_lshl_b64 s[26:27], s[20:21], 20
	s_add_u32 s26, s37, s26
	s_addc_u32 s27, s38, s27
	s_and_b64 s[34:35], s[4:5], exec
	s_cselect_b32 s9, s27, s31
	s_cselect_b32 s21, s26, s30
	s_add_u32 s28, s28, 0x80080
	s_addc_u32 s29, s29, 0
	s_add_u32 s23, s30, 0x100
	s_addc_u32 s54, s31, 0
	s_mov_b32 s56, -2
	s_waitcnt vmcnt(5)
	s_add_u32 s30, s28, 0xfff80080
	s_addc_u32 s31, s29, -1
	s_cmp_eq_u32 s56, 28
	s_cselect_b32 s35, s2, s31
	s_cselect_b32 s34, s3, s30
	s_cselect_b32 s31, s9, s54
	s_cselect_b32 s30, s21, s23
	s_cselect_b32 s100, -1, 0
	s_andn2_b32 s100, s100, s101
	s_add_i32 m0, s43, 0xc000
	global_load_lds_dwordx4 v160, s[28:29]
	s_add_i32 m0, s43, 0xe000
	s_nop 0
	global_load_lds_dwordx4 v162, s[28:29]
	s_waitcnt vmcnt(8)
	s_waitcnt lgkmcnt(0)
	s_setprio 1
	s_barrier
	v_mfma_f32_16x16x32_bf16 v[142:145], v[26:29], v[178:181], 0
	v_mfma_f32_16x16x32_bf16 v[138:141], v[42:45], v[178:181], 0
	v_mfma_f32_16x16x32_bf16 v[126:129], v[26:29], v[186:189], 0
	v_mfma_f32_16x16x32_bf16 v[122:125], v[42:45], v[186:189], 0
	v_mfma_f32_16x16x32_bf16 v[110:113], v[26:29], v[194:197], 0
	v_mfma_f32_16x16x32_bf16 v[106:109], v[42:45], v[194:197], 0
	v_mfma_f32_16x16x32_bf16 v[94:97], v[26:29], v[202:205], 0
	v_mfma_f32_16x16x32_bf16 v[90:93], v[42:45], v[202:205], 0
	v_mfma_f32_16x16x32_bf16 v[142:145], v[30:33], v[182:185], v[142:145]
	v_mfma_f32_16x16x32_bf16 v[138:141], v[46:49], v[182:185], v[138:141]
	v_mfma_f32_16x16x32_bf16 v[126:129], v[30:33], v[190:193], v[126:129]
	v_mfma_f32_16x16x32_bf16 v[122:125], v[46:49], v[190:193], v[122:125]
	v_mfma_f32_16x16x32_bf16 v[110:113], v[30:33], v[198:201], v[110:113]
	v_mfma_f32_16x16x32_bf16 v[106:109], v[46:49], v[198:201], v[106:109]
	v_mfma_f32_16x16x32_bf16 v[94:97], v[30:33], v[206:209], v[94:97]
	v_mfma_f32_16x16x32_bf16 v[90:93], v[46:49], v[206:209], v[90:93]
	s_setprio 0
	s_setprio 1
	v_mfma_f32_16x16x32_bf16 v[134:137], v[146:149], v[178:181], 0
	v_mfma_f32_16x16x32_bf16 v[130:133], v[164:167], v[178:181], 0
	v_mfma_f32_16x16x32_bf16 v[118:121], v[146:149], v[186:189], 0
	v_mfma_f32_16x16x32_bf16 v[114:117], v[164:167], v[186:189], 0
	v_mfma_f32_16x16x32_bf16 v[102:105], v[146:149], v[194:197], 0
	v_mfma_f32_16x16x32_bf16 v[98:101], v[164:167], v[194:197], 0
	v_mfma_f32_16x16x32_bf16 v[86:89], v[146:149], v[202:205], 0
	v_mfma_f32_16x16x32_bf16 v[82:85], v[164:167], v[202:205], 0
	v_mfma_f32_16x16x32_bf16 v[134:137], v[150:153], v[182:185], v[134:137]
	v_mfma_f32_16x16x32_bf16 v[130:133], v[168:171], v[182:185], v[130:133]
	v_mfma_f32_16x16x32_bf16 v[118:121], v[150:153], v[190:193], v[118:121]
	v_mfma_f32_16x16x32_bf16 v[114:117], v[168:171], v[190:193], v[114:117]
	v_mfma_f32_16x16x32_bf16 v[102:105], v[150:153], v[198:201], v[102:105]
	v_mfma_f32_16x16x32_bf16 v[98:101], v[168:171], v[198:201], v[98:101]
	v_mfma_f32_16x16x32_bf16 v[86:89], v[150:153], v[206:209], v[86:89]
	v_mfma_f32_16x16x32_bf16 v[82:85], v[168:171], v[206:209], v[82:85]
	s_barrier
	s_setprio 0
	s_mov_b32 m0, s39
	v_lshl_add_u64 v[210:211], s[30:31], 0, v[0:1]
	s_add_u32 s72, s30, 0x80000
	s_addc_u32 s73, s31, 0
	ds_read_b128 v[178:181], v174 offset:16384
	ds_read_b128 v[182:185], v174 offset:17408
	ds_read_b128 v[186:189], v174 offset:18432
	ds_read_b128 v[190:193], v174 offset:19456
	ds_read_b128 v[194:197], v174 offset:20480
	ds_read_b128 v[198:201], v174 offset:21504
	ds_read_b128 v[202:205], v174 offset:22528
	ds_read_b128 v[206:209], v174 offset:23552
	s_cmp_lg_u32 s100, 0
	s_cbranch_scc1 .Ltl_ic_0s_p
	global_load_lds_dwordx4 v0, s[30:31]
	v_lshl_add_u64 v[212:213], s[30:31], 0, v[158:159]
	s_mov_b32 m0, s40
	s_nop 0
	global_load_lds_dwordx4 v158, s[30:31]
	s_mov_b32 m0, s41
	v_lshl_add_u64 v[216:217], s[34:35], 0, v[156:157]
	global_load_lds_dwordx4 v0, s[72:73]
	s_mov_b32 m0, s42
	s_nop 0
	global_load_lds_dwordx4 v158, s[72:73]
	v_lshl_add_u64 v[214:215], s[34:35], 0, v[154:155]
	s_mov_b32 m0, s43
	s_nop 0
	global_load_lds_dwordx4 v154, s[34:35]
	s_mov_b32 m0, s44
	s_nop 0
	global_load_lds_dwordx4 v156, s[34:35]
	s_waitcnt vmcnt(8)
	s_branch .Ltl_ic_0d_p

;     __device__ __forceinline__ size_t aoff(const Unit& u) const { return (size_t)u.pm * bm * lda * 2; }
;     __device__ __forceinline__ size_t boff(const Unit& u) const { return (size_t)u.pn * BM * ldb * 2; }
;     __device__ __forceinline__ size_t aoff(const Unit& u) const { return ((size_t)u.pm * BM * lda + (size_t)u.pn * akoff) * 2; }
;     __device__ __forceinline__ size_t boff(const Unit& u) const { return (size_t)u.pn * BM * ldb * 2; }
;     __device__ __forceinline__ size_t aoff(const Unit& u) const { return ((size_t)u.pm * BM * lda + (size_t)(u.pn >> 1) * akoff) * 2; }
;     __device__ __forceinline__ size_t boff(const Unit& u) const { return (size_t)u.pn * BM * ldb * 2; }
; #define PG8_STAGE(bufoff, gbase, voff) do { _Pragma("unroll") for (int _i = 0; _i < 2; ++_i) \
;         __builtin_amdgcn_global_load_lds((const unsigned*)((const char*)(gbase) + (voff)[_i]), (LAS unsigned*)(lds + (bufoff) + ldsw + _i * 8192), 16, 0, 0); } while (0)
; #define PG8_SCHED __builtin_amdgcn_sched_barrier(0)
;     __device__ bool next(int i, Unit& u) const {
;         const long L = (long)i * G + c; if (L >= nwg) return false;
;         int wgid = (int)L; { const int q = nwg / NXCD, r = nwg % NXCD, xcd = wgid % NXCD, off = wgid / NXCD; wgid = (xcd < r ? xcd * (q + 1) : r * (q + 1) + (xcd - r) * q) + off; }
;         const int nig = WGM * nN, gid = wgid / nig, fm = gid * WGM, gsz = (nM - fm) < WGM ? (nM - fm) : WGM;
;         u.pm = fm + ((wgid % nig) % gsz); u.pn = (wgid % nig) / gsz; return true;
;     }
;     ...
;         const bool has_next = S.next(ui + 1, nxt);
;         const char* nA = has_next ? (const char*)g.A + S.aoff(nxt) : cA; const char* nB = has_next ? (const char*)g.Bt + S.boff(nxt) : cB;
;         if constexpr (Epi::PRE) E.pre(lds, cur, wid);
;         for (int t = 0; t < nt; t += 2) {
;             const bool last = (t == nt - 2);
;             const char* a1 = cA + (size_t)(t + 1) * kstep;
;             const char* a2 = last ? nA : cA + (size_t)(t + 2) * kstep; const char* b2 = last ? nB : cB + (size_t)(t + 2) * kstep;
;             const char* a3 = a2 + kstep; const char* b3 = b2 + kstep;
;             if constexpr (SP2) {
;             PG8_LDB(B0, 0, 0); PG8_LDB(B1, 0, 1); PG8_SCHED; PG8_LDA(At, 0, 0); PG8_STAGE(PG8_SA(1, 1), a1 + hstepA, voffA);
.LBB0_698:
	v_add_u32_e32 v0, s50, v146
	ds_read_b128 v[138:141], v0
	ds_read_b128 v[142:145], v0 offset:1024
	ds_read_b128 v[148:151], v0 offset:2048
	ds_read_b128 v[152:155], v0 offset:3072
	v_add_u32_e32 v0, s54, v146
	ds_read_b128 v[156:159], v0
	ds_read_b128 v[160:163], v0 offset:1024
	ds_read_b128 v[164:167], v0 offset:2048
	ds_read_b128 v[168:171], v0 offset:3072
	ds_read_b128 v[172:175], v147
	ds_read_b128 v[176:179], v147 offset:1024
	ds_read_b128 v[180:183], v147 offset:2048
	ds_read_b128 v[184:187], v147 offset:3072
	ds_read_b128 v[188:191], v147 offset:4096
	ds_read_b128 v[192:195], v147 offset:5120
	ds_read_b128 v[196:199], v147 offset:6144
	ds_read_b128 v[200:203], v147 offset:7168
	s_add_i32 s23, s23, 1
	s_mul_i32 s2, s23, s75
	s_mul_hi_u32 s3, s23, s53
	s_add_i32 s3, s3, s2
	s_mul_i32 s2, s23, s53
	v_readlane_b32 s4, v255, 29
	s_add_u32 s2, s2, s4
	s_addc_u32 s3, s3, s78
	v_mov_b64_e32 v[2:3], 0x288
	v_cmp_lt_i64_e64 s[4:5], s[2:3], v[2:3]
	v_mov_b64_e32 v[2:3], 0x287
	v_cmp_gt_i64_e32 vcc, s[2:3], v[2:3]
	s_nop 3
	s_mov_b32 s101, s4
	s_cbranch_vccnz .LBB0_700
	s_ashr_i32 s3, s2, 31
	s_lshr_b32 s3, s3, 29
	s_add_i32 s3, s2, s3
	s_ashr_i32 s9, s3, 3
	s_and_b32 s3, s3, -8
	s_sub_i32 s2, s2, s3
	s_cmp_lt_i32 s2, 0
	s_movk_i32 s3, 0x52
	s_cselect_b32 s3, s3, 0x51
	s_mul_i32 s2, s2, s3
	s_add_i32 s2, s2, s9
	s_mul_hi_i32 s3, s2, 0x38e38e39
	s_lshr_b32 s9, s3, 31
	s_ashr_i32 s3, s3, 4
	s_add_i32 s3, s3, s9
	s_lshl_b32 s9, s3, 3
	s_sub_i32 s26, 0x48, s9
	s_min_i32 s27, s26, 8
	s_abs_i32 s26, s27
	v_cvt_f32_u32_e32 v0, s26
	s_sub_i32 s29, 0, s26
	s_mulk_i32 s3, 0x48
	s_sub_i32 s2, s2, s3
	v_rcp_iflag_f32_e32 v0, v0
	s_abs_i32 s3, s2
	s_xor_b32 s28, s2, s27
	s_ashr_i32 s28, s28, 31
	v_mul_f32_e32 v0, 0x4f7ffffe, v0
	v_cvt_u32_f32_e32 v0, v0
	s_nop 0
	v_readfirstlane_b32 s30, v0
	s_mul_i32 s29, s29, s30
	s_mul_hi_u32 s29, s30, s29
	s_add_i32 s30, s30, s29
	s_mul_hi_u32 s29, s3, s30
	s_mul_i32 s30, s29, s26
	s_sub_i32 s3, s3, s30
	s_add_i32 s31, s29, 1
	s_sub_i32 s30, s3, s26
	s_cmp_ge_u32 s3, s26
	s_cselect_b32 s29, s31, s29
	s_cselect_b32 s3, s30, s3
	s_add_i32 s30, s29, 1
	s_cmp_ge_u32 s3, s26
	s_cselect_b32 s3, s30, s29
	s_xor_b32 s3, s3, s28
	s_sub_i32 s26, s3, s28
	s_mul_i32 s3, s26, s27
	s_sub_i32 s2, s2, s3
	s_add_i32 s28, s9, s2

;     __device__ __forceinline__ size_t aoff(const Unit& u) const { return (size_t)u.pm * bm * lda * 2; }
;     __device__ __forceinline__ size_t boff(const Unit& u) const { return (size_t)u.pn * BM * ldb * 2; }
;     __device__ __forceinline__ size_t aoff(const Unit& u) const { return ((size_t)u.pm * BM * lda + (size_t)u.pn * akoff) * 2; }
;     __device__ __forceinline__ size_t boff(const Unit& u) const { return (size_t)u.pn * BM * ldb * 2; }
;     __device__ __forceinline__ size_t aoff(const Unit& u) const { return ((size_t)u.pm * BM * lda + (size_t)(u.pn >> 1) * akoff) * 2; }
;     __device__ __forceinline__ size_t boff(const Unit& u) const { return (size_t)u.pn * BM * ldb * 2; }
; #define PG8_STAGE(bufoff, gbase, voff) do { _Pragma("unroll") for (int _i = 0; _i < 2; ++_i) \
;         __builtin_amdgcn_global_load_lds((const unsigned*)((const char*)(gbase) + (voff)[_i]), (LAS unsigned*)(lds + (bufoff) + ldsw + _i * 8192), 16, 0, 0); } while (0)
; #define PG8_LDA(dst, b, h) do { _Pragma("unroll") for (int m = 0; m < NM; ++m) _Pragma("unroll") for (int k = 0; k < 2; ++k) dst[m][k] = *(const LAS bf16x8*)(lds + PG8_SA(b, h) + aoff + m * 2048 + k * 1024); } while (0)
; #define PG8_BAR __builtin_amdgcn_s_barrier()
;     ...
;         const bool has_next = S.next(ui + 1, nxt);
;         const char* nA = has_next ? (const char*)g.A + S.aoff(nxt) : cA; const char* nB = has_next ? (const char*)g.Bt + S.boff(nxt) : cB;
;         if constexpr (Epi::PRE) E.pre(lds, cur, wid);
;         for (int t = 0; t < nt; t += 2) {
;             const bool last = (t == nt - 2);
;             const char* a1 = cA + (size_t)(t + 1) * kstep;
;             const char* a2 = last ? nA : cA + (size_t)(t + 2) * kstep; const char* b2 = last ? nB : cB + (size_t)(t + 2) * kstep;
;             const char* a3 = a2 + kstep; const char* b3 = b2 + kstep;
;             if constexpr (SP2) {
;             PG8_LDB(B0, 0, 0); PG8_LDB(B1, 0, 1); PG8_SCHED; PG8_LDA(At, 0, 0); PG8_STAGE(PG8_SA(1, 1), a1 + hstepA, voffA);
;             PG8_WAIT_V(8); PG8_WAIT_L(0); PG8_BAR; PG8_MMA(0, 0, At, B0); PG8_MMA(0, 1, At, B1); PG8_BAR; PG8_SCHED;
;             PG8_LDA(At, 0, 1); PG8_STAGE(PG8_SB(0, 0), b2, voffB); PG8_STAGE(PG8_SB(0, 1), b2 + hstepB, voffB); PG8_STAGE(PG8_SA(0, 0), a2, voffA);
;             PG8_WAIT_V(8); PG8_WAIT_L(0); PG8_BAR; PG8_MMA(1, 0, At, B0); PG8_MMA(1, 1, At, B1); PG8_BAR; PG8_SCHED;
.LBB0_702:
	s_ashr_i32 s29, s28, 31
	s_lshl_b64 s[2:3], s[28:29], 20
	s_add_u32 s30, s33, s2
	s_addc_u32 s31, s47, s3
	s_and_b64 s[2:3], s[4:5], exec
	s_cselect_b32 s2, s31, s11
	s_cselect_b32 s3, s30, s10
	s_ashr_i32 s27, s26, 31
	s_lshl_b64 s[34:35], s[26:27], 20
	s_add_u32 s34, s48, s34
	s_addc_u32 s35, s49, s35
	s_and_b64 s[36:37], s[4:5], exec
	s_cselect_b32 s9, s35, s13
	s_cselect_b32 s27, s34, s12
	s_add_u32 s10, s10, 0x80080
	s_addc_u32 s11, s11, 0
	s_add_u32 s29, s12, 0x100
	s_addc_u32 s38, s13, 0
	s_mov_b32 s39, -2
	s_add_u32 s12, s10, 0xfff80080
	s_addc_u32 s13, s11, -1
	s_cmp_eq_u32 s39, 28
	s_cselect_b32 s37, s2, s13
	s_cselect_b32 s36, s3, s12
	s_cselect_b32 s13, s9, s38
	s_cselect_b32 s12, s27, s29
	s_cselect_b32 s100, -1, 0
	s_andn2_b32 s100, s100, s101
	s_add_i32 m0, s58, 0xc000
	global_load_lds_dwordx4 v134, s[10:11]
	s_add_i32 m0, s58, 0xe000
	s_nop 0
	global_load_lds_dwordx4 v136, s[10:11]
	s_waitcnt vmcnt(8)
	s_waitcnt lgkmcnt(0)
	s_setprio 1
	s_barrier
	v_mfma_f32_16x16x32_bf16 v[126:129], v[138:141], v[172:175], 0
	v_mfma_f32_16x16x32_bf16 v[122:125], v[148:151], v[172:175], 0
	v_mfma_f32_16x16x32_bf16 v[110:113], v[138:141], v[180:183], 0
	v_mfma_f32_16x16x32_bf16 v[106:109], v[148:151], v[180:183], 0
	v_mfma_f32_16x16x32_bf16 v[94:97], v[138:141], v[188:191], 0
	v_mfma_f32_16x16x32_bf16 v[90:93], v[148:151], v[188:191], 0
	v_mfma_f32_16x16x32_bf16 v[78:81], v[138:141], v[196:199], 0
	v_mfma_f32_16x16x32_bf16 v[74:77], v[148:151], v[196:199], 0
	v_mfma_f32_16x16x32_bf16 v[126:129], v[142:145], v[176:179], v[126:129]
	v_mfma_f32_16x16x32_bf16 v[122:125], v[152:155], v[176:179], v[122:125]
	v_mfma_f32_16x16x32_bf16 v[110:113], v[142:145], v[184:187], v[110:113]
	v_mfma_f32_16x16x32_bf16 v[106:109], v[152:155], v[184:187], v[106:109]
	v_mfma_f32_16x16x32_bf16 v[94:97], v[142:145], v[192:195], v[94:97]
	v_mfma_f32_16x16x32_bf16 v[90:93], v[152:155], v[192:195], v[90:93]
	v_mfma_f32_16x16x32_bf16 v[78:81], v[142:145], v[200:203], v[78:81]
	v_mfma_f32_16x16x32_bf16 v[74:77], v[152:155], v[200:203], v[74:77]
	s_setprio 0
	s_setprio 1
	v_mfma_f32_16x16x32_bf16 v[118:121], v[156:159], v[172:175], 0
	v_mfma_f32_16x16x32_bf16 v[114:117], v[164:167], v[172:175], 0
	v_mfma_f32_16x16x32_bf16 v[102:105], v[156:159], v[180:183], 0
	v_mfma_f32_16x16x32_bf16 v[98:101], v[164:167], v[180:183], 0
	v_mfma_f32_16x16x32_bf16 v[86:89], v[156:159], v[188:191], 0
	v_mfma_f32_16x16x32_bf16 v[82:85], v[164:167], v[188:191], 0
	v_mfma_f32_16x16x32_bf16 v[70:73], v[156:159], v[196:199], 0
	v_mfma_f32_16x16x32_bf16 v[66:69], v[164:167], v[196:199], 0
	v_mfma_f32_16x16x32_bf16 v[118:121], v[160:163], v[176:179], v[118:121]
	v_mfma_f32_16x16x32_bf16 v[114:117], v[168:171], v[176:179], v[114:117]
	v_mfma_f32_16x16x32_bf16 v[102:105], v[160:163], v[184:187], v[102:105]
	v_mfma_f32_16x16x32_bf16 v[98:101], v[168:171], v[184:187], v[98:101]
	v_mfma_f32_16x16x32_bf16 v[86:89], v[160:163], v[192:195], v[86:89]
	v_mfma_f32_16x16x32_bf16 v[82:85], v[168:171], v[192:195], v[82:85]
	v_mfma_f32_16x16x32_bf16 v[70:73], v[160:163], v[200:203], v[70:73]
	v_mfma_f32_16x16x32_bf16 v[66:69], v[168:171], v[200:203], v[66:69]
	s_barrier
	s_setprio 0
	s_mov_b32 m0, s51
	v_lshl_add_u64 v[204:205], s[12:13], 0, v[130:131]
	s_add_u32 s40, s12, 0x80000
	s_addc_u32 s41, s13, 0
	ds_read_b128 v[172:175], v147 offset:16384
	ds_read_b128 v[176:179], v147 offset:17408
	ds_read_b128 v[180:183], v147 offset:18432
	ds_read_b128 v[184:187], v147 offset:19456
	ds_read_b128 v[188:191], v147 offset:20480
	ds_read_b128 v[192:195], v147 offset:21504
	ds_read_b128 v[196:199], v147 offset:22528
	ds_read_b128 v[200:203], v147 offset:23552
	s_cmp_lg_u32 s100, 0
	s_cbranch_scc1 .Ltl_ia_0s_p
	global_load_lds_dwordx4 v130, s[12:13]
	v_lshl_add_u64 v[206:207], s[12:13], 0, v[132:133]
	s_mov_b32 m0, s52
	s_nop 0
	global_load_lds_dwordx4 v132, s[12:13]
	s_mov_b32 m0, s56
	v_lshl_add_u64 v[210:211], s[36:37], 0, v[132:133]
	global_load_lds_dwordx4 v130, s[40:41]
	s_mov_b32 m0, s57
	s_nop 0
	global_load_lds_dwordx4 v132, s[40:41]
	v_lshl_add_u64 v[208:209], s[36:37], 0, v[130:131]
	s_mov_b32 m0, s58
	s_nop 0
	global_load_lds_dwordx4 v130, s[36:37]
	s_mov_b32 m0, s59
	s_nop 0
	global_load_lds_dwordx4 v132, s[36:37]
	s_waitcnt vmcnt(8)
	s_branch .Ltl_ia_0d_p

;     __device__ __forceinline__ size_t aoff(const Unit& u) const { return (size_t)u.pm * bm * lda * 2; }
;     __device__ __forceinline__ size_t boff(const Unit& u) const { return (size_t)u.pn * BM * ldb * 2; }
;     __device__ __forceinline__ size_t aoff(const Unit& u) const { return ((size_t)u.pm * BM * lda + (size_t)u.pn * akoff) * 2; }
;     __device__ __forceinline__ size_t boff(const Unit& u) const { return (size_t)u.pn * BM * ldb * 2; }
;     __device__ __forceinline__ size_t aoff(const Unit& u) const { return ((size_t)u.pm * BM * lda + (size_t)(u.pn >> 1) * akoff) * 2; }
;     __device__ __forceinline__ size_t boff(const Unit& u) const { return (size_t)u.pn * BM * ldb * 2; }
;     __device__ bool next(int i, Unit& u) const {
;         const long L = (long)i * G + c; if (L >= nwg) return false;
;         int wgid = (int)L; { const int q = nwg / NXCD, r = nwg % NXCD, xcd = wgid % NXCD, off = wgid / NXCD; wgid = (xcd < r ? xcd * (q + 1) : r * (q + 1) + (xcd - r) * q) + off; }
;         const int nig = WGM * nN, gid = wgid / nig, fm = gid * WGM, gsz = (nM - fm) < WGM ? (nM - fm) : WGM;
;         u.pm = fm + ((wgid % nig) % gsz); u.pn = (wgid % nig) / gsz; return true;
;     }
;     ...
;         const bool has_next = S.next(ui + 1, nxt);
;         const char* nA = has_next ? (const char*)g.A + S.aoff(nxt) : cA; const char* nB = has_next ? (const char*)g.Bt + S.boff(nxt) : cB;
;         if constexpr (Epi::PRE) E.pre(lds, cur, wid);
;         for (int t = 0; t < nt; t += 2) {
;             const bool last = (t == nt - 2);
;             const char* a1 = cA + (size_t)(t + 1) * kstep;
;             const char* a2 = last ? nA : cA + (size_t)(t + 2) * kstep; const char* b2 = last ? nB : cB + (size_t)(t + 2) * kstep;
;             const char* a3 = a2 + kstep; const char* b3 = b2 + kstep;
;             if constexpr (SP2) {
;             PG8_LDB(B0, 0, 0); PG8_LDB(B1, 0, 1); PG8_SCHED; PG8_LDA(At, 0, 0); PG8_STAGE(PG8_SA(1, 1), a1 + hstepA, voffA);
;             PG8_WAIT_V(8); PG8_WAIT_L(0); PG8_BAR; PG8_MMA(0, 0, At, B0); PG8_MMA(0, 1, At, B1); PG8_BAR; PG8_SCHED;
;             PG8_LDA(At, 0, 1); PG8_STAGE(PG8_SB(0, 0), b2, voffB); PG8_STAGE(PG8_SB(0, 1), b2 + hstepB, voffB); PG8_STAGE(PG8_SA(0, 0), a2, voffA);
;             PG8_WAIT_V(8); PG8_WAIT_L(0); PG8_BAR; PG8_MMA(1, 0, At, B0); PG8_MMA(1, 1, At, B1); PG8_BAR; PG8_SCHED;
.LBB0_1189:
	v_add_u32_e32 v0, s49, v216
	ds_read_b128 v[10:13], v0
	ds_read_b128 v[14:17], v0 offset:1024
	ds_read_b128 v[18:21], v0 offset:2048
	ds_read_b128 v[22:25], v0 offset:3072
	v_add_u32_e32 v0, s58, v216
	ds_read_b128 v[26:29], v0
	ds_read_b128 v[30:33], v0 offset:1024
	ds_read_b128 v[42:45], v0 offset:2048
	ds_read_b128 v[46:49], v0 offset:3072
	ds_read_b128 v[50:53], v217
	ds_read_b128 v[54:57], v217 offset:1024
	ds_read_b128 v[58:61], v217 offset:2048
	ds_read_b128 v[62:65], v217 offset:3072
	ds_read_b128 v[178:181], v217 offset:4096
	ds_read_b128 v[182:185], v217 offset:5120
	ds_read_b128 v[198:201], v217 offset:6144
	ds_read_b128 v[208:211], v217 offset:7168
	s_add_i32 s47, s47, 1
	s_mul_i32 s2, s47, s92
	s_mul_hi_u32 s3, s47, s53
	s_add_i32 s3, s3, s2
	s_mul_i32 s2, s47, s53
	v_readlane_b32 s4, v255, 29
	s_add_u32 s2, s2, s4
	s_addc_u32 s3, s3, s93
	v_mov_b64_e32 v[2:3], 0x1b0
	v_cmp_lt_i64_e64 s[4:5], s[2:3], v[2:3]
	v_mov_b64_e32 v[2:3], 0x1af
	v_cmp_gt_i64_e32 vcc, s[2:3], v[2:3]
	s_nop 3
	s_mov_b32 s101, s4
	s_cbranch_vccnz .LBB0_1191
	s_ashr_i32 s3, s2, 31
	s_lshr_b32 s3, s3, 29
	s_add_i32 s3, s2, s3
	s_ashr_i32 s7, s3, 3
	s_and_b32 s3, s3, -8
	s_sub_i32 s2, s2, s3
	s_cmp_lt_i32 s2, 0
	s_cselect_b32 s3, 55, 54
	s_mul_i32 s2, s2, s3
	s_add_i32 s2, s2, s7
	s_mul_hi_i32 s3, s2, 0x2aaaaaab
	s_lshr_b32 s7, s3, 31
	s_ashr_i32 s3, s3, 3
	s_add_i32 s3, s3, s7
	s_lshl_b32 s7, s3, 3
	s_sub_i32 s9, 0x48, s7
	s_min_i32 s9, s9, 8
	s_abs_i32 s24, s9
	v_cvt_f32_u32_e32 v0, s24
	s_sub_i32 s26, 0, s24
	s_mul_i32 s3, s3, 48
	s_sub_i32 s2, s2, s3
	v_rcp_iflag_f32_e32 v0, v0
	s_abs_i32 s3, s2
	s_xor_b32 s25, s2, s9
	s_ashr_i32 s25, s25, 31
	v_mul_f32_e32 v0, 0x4f7ffffe, v0
	v_cvt_u32_f32_e32 v0, v0
	s_nop 0
	v_readfirstlane_b32 s27, v0
	s_mul_i32 s26, s26, s27
	s_mul_hi_u32 s26, s27, s26
	s_add_i32 s27, s27, s26
	s_mul_hi_u32 s26, s3, s27
	s_mul_i32 s27, s26, s24
	s_sub_i32 s3, s3, s27
	s_add_i32 s28, s26, 1
	s_sub_i32 s27, s3, s24
	s_cmp_ge_u32 s3, s24
	s_cselect_b32 s26, s28, s26
	s_cselect_b32 s3, s27, s3
	s_add_i32 s27, s26, 1
	s_cmp_ge_u32 s3, s24
	s_cselect_b32 s3, s27, s26
	s_xor_b32 s3, s3, s25
	s_sub_i32 s24, s3, s25
	s_mul_i32 s3, s24, s9
	s_sub_i32 s2, s2, s3
	s_add_i32 s26, s7, s2
.LBB0_1191:
	s_ashr_i32 s27, s26, 31
	s_lshl_b64 s[2:3], s[26:27], 18
	s_add_u32 s28, s33, s2
	s_addc_u32 s29, s43, s3
	s_and_b64 s[2:3], s[4:5], exec
	s_cselect_b32 s2, s29, s11
	s_cselect_b32 s3, s28, s10
	s_ashr_i32 s25, s24, 31
	s_lshl_b64 s[30:31], s[24:25], 18
	s_add_u32 s30, s44, s30
	s_addc_u32 s31, s45, s31
	s_and_b64 s[56:57], s[4:5], exec
	s_cselect_b32 s7, s31, s13
	s_cselect_b32 s27, s30, s12
	s_lshl_b32 s8, s8, 8
	s_ashr_i32 s9, s8, 31
	s_lshl_b64 s[56:57], s[8:9], 2
	s_add_u32 s56, s94, s56
	v_mbcnt_lo_u32_b32 v0, -1, 0
	v_mbcnt_hi_u32_b32 v0, -1, v0
	s_addc_u32 s57, s95, s57
	v_lshlrev_b32_e32 v2, 2, v0
	v_ashrrev_i32_e32 v3, 31, v2
	s_lshl_b32 s25, s34, 13
	v_lshl_add_u64 v[2:3], v[2:3], 2, s[56:57]
	s_add_i32 m0, s81, s25
	s_add_u32 s10, s10, 0x20080
	global_load_lds_dwordx4 v[2:3], off
	s_addc_u32 s11, s11, 0
	s_add_u32 s9, s12, 0x100
	s_addc_u32 s52, s13, 0
	s_mov_b32 s54, -2
	s_add_u32 s12, s10, 0xfffe0080
	s_addc_u32 s13, s11, -1
	s_cmp_eq_u32 s54, 4
	s_cselect_b32 s35, s2, s13
	s_cselect_b32 s34, s3, s12
	s_cselect_b32 s13, s7, s52
	s_cselect_b32 s12, s27, s9
	s_cselect_b32 s100, -1, 0
	s_andn2_b32 s100, s100, s101
	s_add_i32 m0, s62, 0xc000
	global_load_lds_dwordx4 v194, s[10:11]
	s_add_i32 m0, s62, 0xe000
	s_nop 0
	global_load_lds_dwordx4 v196, s[10:11]
	s_waitcnt vmcnt(8)
	s_waitcnt lgkmcnt(0)
	s_setprio 1
	s_barrier
	v_mfma_f32_16x16x32_bf16 v[38:41], v[10:13], v[50:53], 0
	v_mfma_f32_16x16x32_bf16 v[34:37], v[18:21], v[50:53], 0
	v_mfma_f32_16x16x32_bf16 v[174:177], v[10:13], v[58:61], 0
	v_mfma_f32_16x16x32_bf16 v[170:173], v[18:21], v[58:61], 0
	v_mfma_f32_16x16x32_bf16 v[158:161], v[10:13], v[178:181], 0
	v_mfma_f32_16x16x32_bf16 v[154:157], v[18:21], v[178:181], 0
	v_mfma_f32_16x16x32_bf16 v[142:145], v[10:13], v[198:201], 0
	v_mfma_f32_16x16x32_bf16 v[138:141], v[18:21], v[198:201], 0
	v_mfma_f32_16x16x32_bf16 v[38:41], v[14:17], v[54:57], v[38:41]
	v_mfma_f32_16x16x32_bf16 v[34:37], v[22:25], v[54:57], v[34:37]
	v_mfma_f32_16x16x32_bf16 v[174:177], v[14:17], v[62:65], v[174:177]
	v_mfma_f32_16x16x32_bf16 v[170:173], v[22:25], v[62:65], v[170:173]
	v_mfma_f32_16x16x32_bf16 v[158:161], v[14:17], v[182:185], v[158:161]
	v_mfma_f32_16x16x32_bf16 v[154:157], v[22:25], v[182:185], v[154:157]
	v_mfma_f32_16x16x32_bf16 v[142:145], v[14:17], v[208:211], v[142:145]
	v_mfma_f32_16x16x32_bf16 v[138:141], v[22:25], v[208:211], v[138:141]
	s_setprio 0
	s_setprio 1
	v_mfma_f32_16x16x32_bf16 v[6:9], v[26:29], v[50:53], 0
	v_mfma_f32_16x16x32_bf16 v[2:5], v[42:45], v[50:53], 0
	v_mfma_f32_16x16x32_bf16 v[6:9], v[30:33], v[54:57], v[6:9]
	v_mfma_f32_16x16x32_bf16 v[2:5], v[46:49], v[54:57], v[2:5]
	v_mfma_f32_16x16x32_bf16 v[50:53], v[26:29], v[58:61], 0
	v_mfma_f32_16x16x32_bf16 v[54:57], v[42:45], v[58:61], 0
	v_mfma_f32_16x16x32_bf16 v[134:137], v[26:29], v[198:201], 0
	v_mfma_f32_16x16x32_bf16 v[130:133], v[42:45], v[198:201], 0
	v_mfma_f32_16x16x32_bf16 v[50:53], v[30:33], v[62:65], v[50:53]
	v_mfma_f32_16x16x32_bf16 v[54:57], v[46:49], v[62:65], v[54:57]
	v_mfma_f32_16x16x32_bf16 v[58:61], v[26:29], v[178:181], 0
	v_mfma_f32_16x16x32_bf16 v[62:65], v[42:45], v[178:181], 0
	v_mfma_f32_16x16x32_bf16 v[134:137], v[30:33], v[208:211], v[134:137]
	v_mfma_f32_16x16x32_bf16 v[130:133], v[46:49], v[208:211], v[130:133]
	v_mfma_f32_16x16x32_bf16 v[58:61], v[30:33], v[182:185], v[58:61]
	v_mfma_f32_16x16x32_bf16 v[62:65], v[46:49], v[182:185], v[62:65]
	s_barrier
	s_setprio 0
	s_mov_b32 m0, s50
	v_lshl_add_u64 v[202:203], s[12:13], 0, v[188:189]
	s_add_u32 s56, s12, 0x20000
	s_addc_u32 s57, s13, 0
	ds_read_b128 v[146:149], v217 offset:16384
	ds_read_b128 v[150:153], v217 offset:17408
	ds_read_b128 v[162:165], v217 offset:18432
	ds_read_b128 v[166:169], v217 offset:19456
	ds_read_b128 v[178:181], v217 offset:20480
	ds_read_b128 v[182:185], v217 offset:21504
	ds_read_b128 v[198:201], v217 offset:22528
	ds_read_b128 v[208:211], v217 offset:23552
	s_cmp_lg_u32 s100, 0
	s_cbranch_scc1 .Ltl_qp_0s_p
	global_load_lds_dwordx4 v188, s[12:13]
	v_lshl_add_u64 v[204:205], s[12:13], 0, v[192:193]
	s_mov_b32 m0, s51
	s_nop 0
	global_load_lds_dwordx4 v192, s[12:13]
	s_mov_b32 m0, s59
	v_lshl_add_u64 v[222:223], s[34:35], 0, v[190:191]
	global_load_lds_dwordx4 v188, s[56:57]
	s_mov_b32 m0, s60
	s_nop 0
	global_load_lds_dwordx4 v192, s[56:57]
	v_lshl_add_u64 v[206:207], s[34:35], 0, v[186:187]
	s_mov_b32 m0, s62
	s_nop 0
	global_load_lds_dwordx4 v186, s[34:35]
	s_mov_b32 m0, s63
	s_nop 0
	global_load_lds_dwordx4 v190, s[34:35]
	s_waitcnt vmcnt(8)
	s_branch .Ltl_qp_0d_p

;     __device__ __forceinline__ size_t aoff(const Unit& u) const { return (size_t)u.pm * bm * lda * 2; }
;     __device__ __forceinline__ size_t boff(const Unit& u) const { return (size_t)u.pn * BM * ldb * 2; }
;     __device__ __forceinline__ size_t aoff(const Unit& u) const { return ((size_t)u.pm * BM * lda + (size_t)u.pn * akoff) * 2; }
;     __device__ __forceinline__ size_t boff(const Unit& u) const { return (size_t)u.pn * BM * ldb * 2; }
;     __device__ __forceinline__ size_t aoff(const Unit& u) const { return ((size_t)u.pm * BM * lda + (size_t)(u.pn >> 1) * akoff) * 2; }
;     __device__ __forceinline__ size_t boff(const Unit& u) const { return (size_t)u.pn * BM * ldb * 2; }
; #define PG8_STAGE(bufoff, gbase, voff) do { _Pragma("unroll") for (int _i = 0; _i < 2; ++_i) \
;         __builtin_amdgcn_global_load_lds((const unsigned*)((const char*)(gbase) + (voff)[_i]), (LAS unsigned*)(lds + (bufoff) + ldsw + _i * 8192), 16, 0, 0); } while (0)
; #define PG8_SCHED __builtin_amdgcn_sched_barrier(0)
;     __device__ bool next(int i, Unit& u) const {
;         const long L = (long)i * G + c; if (L >= nwg) return false;
;         int wgid = (int)L; { const int q = nwg / NXCD, r = nwg % NXCD, xcd = wgid % NXCD, off = wgid / NXCD; wgid = (xcd < r ? xcd * (q + 1) : r * (q + 1) + (xcd - r) * q) + off; }
;         const int nig = WGM * nN, gid = wgid / nig, fm = gid * WGM, gsz = (nM - fm) < WGM ? (nM - fm) : WGM;
;         u.pm = fm + ((wgid % nig) % gsz); u.pn = (wgid % nig) / gsz; return true;
;     }
;     ...
;         const bool has_next = S.next(ui + 1, nxt);
;         const char* nA = has_next ? (const char*)g.A + S.aoff(nxt) : cA; const char* nB = has_next ? (const char*)g.Bt + S.boff(nxt) : cB;
;         if constexpr (Epi::PRE) E.pre(lds, cur, wid);
;         for (int t = 0; t < nt; t += 2) {
;             const bool last = (t == nt - 2);
;             const char* a1 = cA + (size_t)(t + 1) * kstep;
;             const char* a2 = last ? nA : cA + (size_t)(t + 2) * kstep; const char* b2 = last ? nB : cB + (size_t)(t + 2) * kstep;
;             const char* a3 = a2 + kstep; const char* b3 = b2 + kstep;
;             if constexpr (SP2) {
;             PG8_LDB(B0, 0, 0); PG8_LDB(B1, 0, 1); PG8_SCHED; PG8_LDA(At, 0, 0); PG8_STAGE(PG8_SA(1, 1), a1 + hstepA, voffA);
.LBB0_1445:
	v_add_u32_e32 v140, s31, v142
	ds_read_b128 v[144:147], v140
	ds_read_b128 v[148:151], v140 offset:1024
	ds_read_b128 v[152:155], v140 offset:2048
	ds_read_b128 v[156:159], v140 offset:3072
	v_add_u32_e32 v140, s35, v142
	ds_read_b128 v[160:163], v140
	ds_read_b128 v[164:167], v140 offset:1024
	ds_read_b128 v[168:171], v140 offset:2048
	ds_read_b128 v[172:175], v140 offset:3072
	ds_read_b128 v[176:179], v143
	ds_read_b128 v[180:183], v143 offset:1024
	ds_read_b128 v[184:187], v143 offset:2048
	ds_read_b128 v[188:191], v143 offset:3072
	ds_read_b128 v[192:195], v143 offset:4096
	ds_read_b128 v[196:199], v143 offset:5120
	ds_read_b128 v[200:203], v143 offset:6144
	ds_read_b128 v[208:211], v143 offset:7168
	s_add_i32 s69, s69, 1
	s_mul_i32 s2, s69, s68
	s_mul_hi_u32 s3, s69, s53
	s_add_i32 s3, s3, s2
	s_mul_i32 s2, s69, s53
	v_readlane_b32 s4, v255, 29
	s_add_u32 s2, s2, s4
	s_addc_u32 s3, s3, s26
	v_mov_b64_e32 v[2:3], 0x200
	v_cmp_lt_i64_e64 s[6:7], s[2:3], v[2:3]
	v_mov_b64_e32 v[2:3], 0x1ff
	v_cmp_gt_i64_e32 vcc, s[2:3], v[2:3]
	s_nop 3
	s_mov_b32 s101, s6
	s_cbranch_vccnz .LBB0_1451
	s_ashr_i32 s3, s2, 31
	s_lshr_b32 s3, s3, 29
	s_add_i32 s4, s2, s3
	s_and_b32 s3, s4, -8
	s_sub_i32 s5, s2, s3
	s_cmp_gt_i32 s5, -1
	s_mov_b64 s[2:3], -1
	s_cbranch_scc0 .LBB0_1448
	s_lshl_b32 s14, s5, 6
	s_mov_b64 s[2:3], 0

;     __device__ __forceinline__ size_t aoff(const Unit& u) const { return (size_t)u.pm * bm * lda * 2; }
;     __device__ __forceinline__ size_t boff(const Unit& u) const { return (size_t)u.pn * BM * ldb * 2; }
;     __device__ __forceinline__ size_t aoff(const Unit& u) const { return ((size_t)u.pm * BM * lda + (size_t)u.pn * akoff) * 2; }
;     __device__ __forceinline__ size_t boff(const Unit& u) const { return (size_t)u.pn * BM * ldb * 2; }
;     __device__ __forceinline__ size_t aoff(const Unit& u) const { return ((size_t)u.pm * BM * lda + (size_t)(u.pn >> 1) * akoff) * 2; }
;     __device__ __forceinline__ size_t boff(const Unit& u) const { return (size_t)u.pn * BM * ldb * 2; }
; #define PG8_STAGE(bufoff, gbase, voff) do { _Pragma("unroll") for (int _i = 0; _i < 2; ++_i) \
;         __builtin_amdgcn_global_load_lds((const unsigned*)((const char*)(gbase) + (voff)[_i]), (LAS unsigned*)(lds + (bufoff) + ldsw + _i * 8192), 16, 0, 0); } while (0)
; #define PG8_LDA(dst, b, h) do { _Pragma("unroll") for (int m = 0; m < NM; ++m) _Pragma("unroll") for (int k = 0; k < 2; ++k) dst[m][k] = *(const LAS bf16x8*)(lds + PG8_SA(b, h) + aoff + m * 2048 + k * 1024); } while (0)
; #define PG8_BAR __builtin_amdgcn_s_barrier()
;     ...
;         const bool has_next = S.next(ui + 1, nxt);
;         const char* nA = has_next ? (const char*)g.A + S.aoff(nxt) : cA; const char* nB = has_next ? (const char*)g.Bt + S.boff(nxt) : cB;
;         if constexpr (Epi::PRE) E.pre(lds, cur, wid);
;         for (int t = 0; t < nt; t += 2) {
;             const bool last = (t == nt - 2);
;             const char* a1 = cA + (size_t)(t + 1) * kstep;
;             const char* a2 = last ? nA : cA + (size_t)(t + 2) * kstep; const char* b2 = last ? nB : cB + (size_t)(t + 2) * kstep;
;             const char* a3 = a2 + kstep; const char* b3 = b2 + kstep;
;             if constexpr (SP2) {
;             PG8_LDB(B0, 0, 0); PG8_LDB(B1, 0, 1); PG8_SCHED; PG8_LDA(At, 0, 0); PG8_STAGE(PG8_SA(1, 1), a1 + hstepA, voffA);
;             PG8_WAIT_V(8); PG8_WAIT_L(0); PG8_BAR; PG8_MMA(0, 0, At, B0); PG8_MMA(0, 1, At, B1); PG8_BAR; PG8_SCHED;
;             PG8_LDA(At, 0, 1); PG8_STAGE(PG8_SB(0, 0), b2, voffB); PG8_STAGE(PG8_SB(0, 1), b2 + hstepB, voffB); PG8_STAGE(PG8_SA(0, 0), a2, voffA);
;             PG8_WAIT_V(8); PG8_WAIT_L(0); PG8_BAR; PG8_MMA(1, 0, At, B0); PG8_MMA(1, 1, At, B1); PG8_BAR; PG8_SCHED;
.LBB0_1453:
	s_ashr_i32 s15, s14, 31
	s_lshl_b64 s[2:3], s[14:15], 18
	s_add_u32 s18, s29, s2
	s_addc_u32 s19, s30, s3
	s_and_b64 s[2:3], s[6:7], exec
	s_cselect_b32 s2, s19, s23
	s_cselect_b32 s3, s18, s22
	s_add_u32 s15, s22, 0x100
	s_addc_u32 s60, s23, 0
	s_mov_b32 s73, -2
	s_add_u32 s6, s20, 0x100
	s_addc_u32 s7, s21, 0
	s_cmp_eq_u32 s73, 4
	s_cselect_b32 s25, s17, s7
	s_cselect_b32 s24, s16, s6
	s_cselect_b32 s23, s2, s60
	s_cselect_b32 s22, s3, s15
	s_cselect_b32 s100, -1, 0
	s_andn2_b32 s100, s100, s101
	s_add_i32 m0, s45, 0xc000
	global_load_lds_dwordx4 v136, s[20:21]
	s_add_i32 m0, s45, 0xe000
	s_nop 0
	global_load_lds_dwordx4 v138, s[20:21]
	s_waitcnt vmcnt(8)
	s_waitcnt lgkmcnt(0)
	s_setprio 1
	s_barrier
	v_mfma_f32_16x16x32_bf16 v[126:129], v[144:147], v[176:179], 0
	v_mfma_f32_16x16x32_bf16 v[122:125], v[152:155], v[176:179], 0
	v_mfma_f32_16x16x32_bf16 v[118:121], v[144:147], v[184:187], 0
	v_mfma_f32_16x16x32_bf16 v[114:117], v[152:155], v[184:187], 0
	v_mfma_f32_16x16x32_bf16 v[110:113], v[144:147], v[192:195], 0
	v_mfma_f32_16x16x32_bf16 v[106:109], v[152:155], v[192:195], 0
	v_mfma_f32_16x16x32_bf16 v[102:105], v[144:147], v[200:203], 0
	v_mfma_f32_16x16x32_bf16 v[98:101], v[152:155], v[200:203], 0
	v_mfma_f32_16x16x32_bf16 v[126:129], v[148:151], v[180:183], v[126:129]
	v_mfma_f32_16x16x32_bf16 v[122:125], v[156:159], v[180:183], v[122:125]
	v_mfma_f32_16x16x32_bf16 v[118:121], v[148:151], v[188:191], v[118:121]
	v_mfma_f32_16x16x32_bf16 v[114:117], v[156:159], v[188:191], v[114:117]
	v_mfma_f32_16x16x32_bf16 v[110:113], v[148:151], v[196:199], v[110:113]
	v_mfma_f32_16x16x32_bf16 v[106:109], v[156:159], v[196:199], v[106:109]
	v_mfma_f32_16x16x32_bf16 v[102:105], v[148:151], v[208:211], v[102:105]
	v_mfma_f32_16x16x32_bf16 v[98:101], v[156:159], v[208:211], v[98:101]
	s_setprio 0
	s_setprio 1
	v_mfma_f32_16x16x32_bf16 v[62:65], v[160:163], v[176:179], 0
	v_mfma_f32_16x16x32_bf16 v[58:61], v[168:171], v[176:179], 0
	v_mfma_f32_16x16x32_bf16 v[54:57], v[160:163], v[184:187], 0
	v_mfma_f32_16x16x32_bf16 v[50:53], v[168:171], v[184:187], 0
	v_mfma_f32_16x16x32_bf16 v[46:49], v[160:163], v[192:195], 0
	v_mfma_f32_16x16x32_bf16 v[42:45], v[168:171], v[192:195], 0
	v_mfma_f32_16x16x32_bf16 v[38:41], v[160:163], v[200:203], 0
	v_mfma_f32_16x16x32_bf16 v[34:37], v[168:171], v[200:203], 0
	v_mfma_f32_16x16x32_bf16 v[62:65], v[164:167], v[180:183], v[62:65]
	v_mfma_f32_16x16x32_bf16 v[58:61], v[172:175], v[180:183], v[58:61]
	v_mfma_f32_16x16x32_bf16 v[54:57], v[164:167], v[188:191], v[54:57]
	v_mfma_f32_16x16x32_bf16 v[50:53], v[172:175], v[188:191], v[50:53]
	v_mfma_f32_16x16x32_bf16 v[46:49], v[164:167], v[196:199], v[46:49]
	v_mfma_f32_16x16x32_bf16 v[42:45], v[172:175], v[196:199], v[42:45]
	v_mfma_f32_16x16x32_bf16 v[38:41], v[164:167], v[208:211], v[38:41]
	v_mfma_f32_16x16x32_bf16 v[34:37], v[172:175], v[208:211], v[34:37]
	s_barrier
	s_setprio 0
	s_mov_b32 m0, s33
	v_lshl_add_u64 v[140:141], s[22:23], 0, v[0:1]
	s_add_u32 s20, s22, 0x20000
	s_addc_u32 s21, s23, 0
	ds_read_b128 v[176:179], v143 offset:16384
	ds_read_b128 v[180:183], v143 offset:17408
	ds_read_b128 v[184:187], v143 offset:18432
	ds_read_b128 v[188:191], v143 offset:19456
	ds_read_b128 v[192:195], v143 offset:20480
	ds_read_b128 v[196:199], v143 offset:21504
	ds_read_b128 v[200:203], v143 offset:22528
	ds_read_b128 v[208:211], v143 offset:23552
	s_cmp_lg_u32 s100, 0
	s_cbranch_scc1 .Ltl_kv_0s_p
	global_load_lds_dwordx4 v0, s[22:23]
	v_lshl_add_u64 v[204:205], s[22:23], 0, v[134:135]
	s_mov_b32 m0, s34
	s_nop 0
	global_load_lds_dwordx4 v134, s[22:23]
	s_mov_b32 m0, s43
	v_lshl_add_u64 v[212:213], s[24:25], 0, v[132:133]
	global_load_lds_dwordx4 v0, s[20:21]
	s_mov_b32 m0, s44
	s_nop 0
	global_load_lds_dwordx4 v134, s[20:21]
	v_lshl_add_u64 v[206:207], s[24:25], 0, v[130:131]
	s_mov_b32 m0, s45
	s_nop 0
	global_load_lds_dwordx4 v130, s[24:25]
	s_mov_b32 m0, s47
	s_nop 0
	global_load_lds_dwordx4 v132, s[24:25]
	s_waitcnt vmcnt(8)
	s_branch .Ltl_kv_0d_p

;     __device__ __forceinline__ size_t aoff(const Unit& u) const { return (size_t)u.pm * bm * lda * 2; }
;     __device__ __forceinline__ size_t boff(const Unit& u) const { return (size_t)u.pn * BM * ldb * 2; }
;     __device__ __forceinline__ size_t aoff(const Unit& u) const { return ((size_t)u.pm * BM * lda + (size_t)u.pn * akoff) * 2; }
;     __device__ __forceinline__ size_t boff(const Unit& u) const { return (size_t)u.pn * BM * ldb * 2; }
;     __device__ __forceinline__ size_t aoff(const Unit& u) const { return ((size_t)u.pm * BM * lda + (size_t)(u.pn >> 1) * akoff) * 2; }
;     __device__ __forceinline__ size_t boff(const Unit& u) const { return (size_t)u.pn * BM * ldb * 2; }
; #define PG8_STAGE(bufoff, gbase, voff) do { _Pragma("unroll") for (int _i = 0; _i < 2; ++_i) \
;         __builtin_amdgcn_global_load_lds((const unsigned*)((const char*)(gbase) + (voff)[_i]), (LAS unsigned*)(lds + (bufoff) + ldsw + _i * 8192), 16, 0, 0); } while (0)
; #define PG8_SCHED __builtin_amdgcn_sched_barrier(0)
;     __device__ bool next(int i, Unit& u) const {
;         const long L = (long)i * G + c; if (L >= nwg) return false;
;         int wgid = (int)L; { const int q = nwg / NXCD, r = nwg % NXCD, xcd = wgid % NXCD, off = wgid / NXCD; wgid = (xcd < r ? xcd * (q + 1) : r * (q + 1) + (xcd - r) * q) + off; }
;         const int nig = WGM * nN, gid = wgid / nig, fm = gid * WGM, gsz = (nM - fm) < WGM ? (nM - fm) : WGM;
;         u.pm = fm + ((wgid % nig) % gsz); u.pn = (wgid % nig) / gsz; return true;
;     }
;     ...
;         const bool has_next = S.next(ui + 1, nxt);
;         const char* nA = has_next ? (const char*)g.A + S.aoff(nxt) : cA; const char* nB = has_next ? (const char*)g.Bt + S.boff(nxt) : cB;
;         if constexpr (Epi::PRE) E.pre(lds, cur, wid);
;         for (int t = 0; t < nt; t += 2) {
;             const bool last = (t == nt - 2);
;             const char* a1 = cA + (size_t)(t + 1) * kstep;
;             const char* a2 = last ? nA : cA + (size_t)(t + 2) * kstep; const char* b2 = last ? nB : cB + (size_t)(t + 2) * kstep;
;             const char* a3 = a2 + kstep; const char* b3 = b2 + kstep;
;             if constexpr (SP2) {
;             PG8_LDB(B0, 0, 0); PG8_LDB(B1, 0, 1); PG8_SCHED; PG8_LDA(At, 0, 0); PG8_STAGE(PG8_SA(1, 1), a1 + hstepA, voffA);
.LBB0_1645:
	v_add_u32_e32 v102, s21, v166
	v_add_u32_e32 v126, s31, v166
	ds_read_b128 v[90:93], v102
	ds_read_b128 v[94:97], v102 offset:1024
	ds_read_b128 v[98:101], v102 offset:2048
	ds_read_b128 v[102:105], v102 offset:3072
	ds_read_b128 v[114:117], v126
	ds_read_b128 v[118:121], v126 offset:1024
	ds_read_b128 v[122:125], v126 offset:2048
	ds_read_b128 v[126:129], v126 offset:3072
	ds_read_b128 v[130:133], v167
	ds_read_b128 v[134:137], v167 offset:1024
	ds_read_b128 v[138:141], v167 offset:2048
	ds_read_b128 v[152:155], v167 offset:3072
	ds_read_b128 v[156:159], v167 offset:4096
	ds_read_b128 v[160:163], v167 offset:5120
	s_add_i32 s54, s54, 1
	s_mul_i32 s2, s54, s48
	s_mul_hi_u32 s3, s54, s53
	s_add_i32 s3, s3, s2
	s_mul_i32 s2, s54, s53
	v_readlane_b32 s6, v255, 29
	s_add_u32 s2, s2, s6
	s_addc_u32 s3, s3, s49
	v_mov_b64_e32 v[2:3], 0x300
	v_cmp_lt_i64_e64 s[8:9], s[2:3], v[2:3]
	v_mov_b64_e32 v[2:3], 0x2ff
	v_cmp_gt_i64_e32 vcc, s[2:3], v[2:3]
	s_nop 3
	s_mov_b32 s101, s8
	s_cbranch_vccnz .LBB0_1647
	s_ashr_i32 s3, s2, 31
	s_lshr_b32 s3, s3, 29
	s_add_i32 s3, s2, s3
	s_ashr_i32 s6, s3, 3
	s_and_b32 s3, s3, -8
	s_sub_i32 s2, s2, s3
	s_cmp_lt_i32 s2, 0
	s_movk_i32 s3, 0x61
	s_cselect_b32 s3, s3, 0x60
	s_mul_i32 s2, s2, s3
	s_add_i32 s2, s2, s6
	s_ashr_i32 s3, s2, 31
	s_lshr_b32 s3, s3, 26
	s_add_i32 s3, s2, s3
	s_ashr_i32 s6, s3, 6
	s_lshl_b32 s6, s6, 3
	s_sub_i32 s7, 0x60, s6
	s_min_i32 s7, s7, 8
	s_abs_i32 s14, s7
	v_cvt_f32_u32_e32 v2, s14
	s_sub_i32 s16, 0, s14
	s_andn2_b32 s3, s3, 63
	s_sub_i32 s2, s2, s3
	v_rcp_iflag_f32_e32 v2, v2
	s_abs_i32 s3, s2
	s_xor_b32 s15, s2, s7
	s_ashr_i32 s15, s15, 31
	v_mul_f32_e32 v2, 0x4f7ffffe, v2
	v_cvt_u32_f32_e32 v2, v2
	s_nop 0
	v_readfirstlane_b32 s17, v2
	s_mul_i32 s16, s16, s17
	s_mul_hi_u32 s16, s17, s16
	s_add_i32 s17, s17, s16
	s_mul_hi_u32 s16, s3, s17
	s_mul_i32 s17, s16, s14
	s_sub_i32 s3, s3, s17
	s_add_i32 s18, s16, 1
	s_sub_i32 s17, s3, s14
	s_cmp_ge_u32 s3, s14
	s_cselect_b32 s16, s18, s16
	s_cselect_b32 s3, s17, s3
	s_add_i32 s17, s16, 1
	s_cmp_ge_u32 s3, s14
	s_cselect_b32 s3, s17, s16
	s_xor_b32 s3, s3, s15
	s_sub_i32 s14, s3, s15
	s_mul_i32 s3, s14, s7
	s_sub_i32 s2, s2, s3
	s_add_i32 s56, s6, s2

;     __device__ __forceinline__ size_t aoff(const Unit& u) const { return (size_t)u.pm * bm * lda * 2; }
;     __device__ __forceinline__ size_t boff(const Unit& u) const { return (size_t)u.pn * BM * ldb * 2; }
;     __device__ __forceinline__ size_t aoff(const Unit& u) const { return ((size_t)u.pm * BM * lda + (size_t)u.pn * akoff) * 2; }
;     __device__ __forceinline__ size_t boff(const Unit& u) const { return (size_t)u.pn * BM * ldb * 2; }
;     __device__ __forceinline__ size_t aoff(const Unit& u) const { return ((size_t)u.pm * BM * lda + (size_t)(u.pn >> 1) * akoff) * 2; }
;     __device__ __forceinline__ size_t boff(const Unit& u) const { return (size_t)u.pn * BM * ldb * 2; }
; #define PG8_STAGE(bufoff, gbase, voff) do { _Pragma("unroll") for (int _i = 0; _i < 2; ++_i) \
;         __builtin_amdgcn_global_load_lds((const unsigned*)((const char*)(gbase) + (voff)[_i]), (LAS unsigned*)(lds + (bufoff) + ldsw + _i * 8192), 16, 0, 0); } while (0)
; #define PG8_LDA(dst, b, h) do { _Pragma("unroll") for (int m = 0; m < NM; ++m) _Pragma("unroll") for (int k = 0; k < 2; ++k) dst[m][k] = *(const LAS bf16x8*)(lds + PG8_SA(b, h) + aoff + m * 2048 + k * 1024); } while (0)
; #define PG8_LDB(dst, b, h) do { _Pragma("unroll") for (int n = 0; n < 2; ++n) _Pragma("unroll") for (int k = 0; k < 2; ++k) dst[n][k] = *(const LAS bf16x8*)(lds + PG8_SB(b, h) + boff + n * 2048 + k * 1024); } while (0)
; #define PG8_WAIT_V(n) asm volatile("s_waitcnt vmcnt(" #n ")" ::: "memory")
;     ...
;         const bool has_next = S.next(ui + 1, nxt);
;         const char* nA = has_next ? (const char*)g.A + S.aoff(nxt) : cA; const char* nB = has_next ? (const char*)g.Bt + S.boff(nxt) : cB;
;         if constexpr (Epi::PRE) E.pre(lds, cur, wid);
;         for (int t = 0; t < nt; t += 2) {
;             const bool last = (t == nt - 2);
;             const char* a1 = cA + (size_t)(t + 1) * kstep;
;             const char* a2 = last ? nA : cA + (size_t)(t + 2) * kstep; const char* b2 = last ? nB : cB + (size_t)(t + 2) * kstep;
;             const char* a3 = a2 + kstep; const char* b3 = b2 + kstep;
;             if constexpr (SP2) {
;             PG8_LDB(B0, 0, 0); PG8_LDB(B1, 0, 1); PG8_SCHED; PG8_LDA(At, 0, 0); PG8_STAGE(PG8_SA(1, 1), a1 + hstepA, voffA);
;             PG8_WAIT_V(8); PG8_WAIT_L(0); PG8_BAR; PG8_MMA(0, 0, At, B0); PG8_MMA(0, 1, At, B1); PG8_BAR; PG8_SCHED;
.LBB0_1649:
	s_ashr_i32 s15, s14, 31
	s_lshl_b64 s[2:3], s[14:15], 20
	s_add_u32 s18, s5, s2
	s_addc_u32 s19, s26, s3
	s_and_b64 s[2:3], s[8:9], exec
	s_cselect_b32 s2, s19, s23
	s_cselect_b32 s3, s18, s22
	s_add_u32 s8, s24, 0x60080
	s_addc_u32 s9, s25, 0
	s_add_u32 s15, s22, 0x100
	s_addc_u32 s58, s23, 0
	s_mov_b32 s59, -2
	s_waitcnt vmcnt(5)
	s_add_u32 s22, s8, 0xfffa0080
	s_addc_u32 s23, s9, -1
	s_cmp_eq_u32 s59, 28
	s_cselect_b32 s25, s17, s23
	s_cselect_b32 s24, s16, s22
	s_cselect_b32 s23, s2, s58
	s_cselect_b32 s22, s3, s15
	s_cselect_b32 s100, -1, 0
	s_andn2_b32 s100, s100, s101
	s_add_i32 m0, s35, 0xc000
	global_load_lds_dwordx4 v148, s[8:9]
	s_add_i32 m0, s35, 0xe000
	s_nop 0
	s_and_b64 vcc, exec, s[10:11]
	s_cbranch_vccz .Lnm3o_skip0_p
	global_load_lds_dwordx4 v150, s[8:9]
	s_waitcnt vmcnt(8)
	s_branch .Lnm3o_done0_p

;     __device__ __forceinline__ size_t aoff(const Unit& u) const { return (size_t)u.pm * bm * lda * 2; }
;     __device__ __forceinline__ size_t boff(const Unit& u) const { return (size_t)u.pn * BM * ldb * 2; }
;     __device__ __forceinline__ size_t aoff(const Unit& u) const { return ((size_t)u.pm * BM * lda + (size_t)u.pn * akoff) * 2; }
;     __device__ __forceinline__ size_t boff(const Unit& u) const { return (size_t)u.pn * BM * ldb * 2; }
;     __device__ __forceinline__ size_t aoff(const Unit& u) const { return ((size_t)u.pm * BM * lda + (size_t)(u.pn >> 1) * akoff) * 2; }
;     __device__ __forceinline__ size_t boff(const Unit& u) const { return (size_t)u.pn * BM * ldb * 2; }
; #define PG8_STAGE(bufoff, gbase, voff) do { _Pragma("unroll") for (int _i = 0; _i < 2; ++_i) \
;         __builtin_amdgcn_global_load_lds((const unsigned*)((const char*)(gbase) + (voff)[_i]), (LAS unsigned*)(lds + (bufoff) + ldsw + _i * 8192), 16, 0, 0); } while (0)
; #define PG8_SCHED __builtin_amdgcn_sched_barrier(0)
;     __device__ bool next(int i, Unit& u) const {
;         const long L = (long)i * G + c; if (L >= nwg) return false;
;         int wgid = (int)L; { const int q = nwg / NXCD, r = nwg % NXCD, xcd = wgid % NXCD, off = wgid / NXCD; wgid = (xcd < r ? xcd * (q + 1) : r * (q + 1) + (xcd - r) * q) + off; }
;         const int nig = WGM * nN, gid = wgid / nig, fm = gid * WGM, gsz = (nM - fm) < WGM ? (nM - fm) : WGM;
;         u.pm = fm + ((wgid % nig) % gsz); u.pn = (wgid % nig) / gsz; return true;
;     }
;     ...
;         const bool has_next = S.next(ui + 1, nxt);
;         const char* nA = has_next ? (const char*)g.A + S.aoff(nxt) : cA; const char* nB = has_next ? (const char*)g.Bt + S.boff(nxt) : cB;
;         if constexpr (Epi::PRE) E.pre(lds, cur, wid);
;         for (int t = 0; t < nt; t += 2) {
;             const bool last = (t == nt - 2);
;             const char* a1 = cA + (size_t)(t + 1) * kstep;
;             const char* a2 = last ? nA : cA + (size_t)(t + 2) * kstep; const char* b2 = last ? nB : cB + (size_t)(t + 2) * kstep;
;             const char* a3 = a2 + kstep; const char* b3 = b2 + kstep;
;             if constexpr (SP2) {
;             PG8_LDB(B0, 0, 0); PG8_LDB(B1, 0, 1); PG8_SCHED; PG8_LDA(At, 0, 0); PG8_STAGE(PG8_SA(1, 1), a1 + hstepA, voffA);
.LBB0_1770:
	v_add_u32_e32 v0, s64, v208
	ds_read_b128 v[130:133], v0
	ds_read_b128 v[134:137], v0 offset:1024
	ds_read_b128 v[138:141], v0 offset:2048
	ds_read_b128 v[142:145], v0 offset:3072
	v_add_u32_e32 v0, s70, v208
	ds_read_b128 v[146:149], v0
	ds_read_b128 v[150:153], v0 offset:1024
	ds_read_b128 v[154:157], v0 offset:2048
	ds_read_b128 v[158:161], v0 offset:3072
	ds_read_b128 v[162:165], v209
	ds_read_b128 v[166:169], v209 offset:1024
	ds_read_b128 v[170:173], v209 offset:2048
	ds_read_b128 v[174:177], v209 offset:3072
	ds_read_b128 v[190:193], v209 offset:4096
	ds_read_b128 v[194:197], v209 offset:5120
	ds_read_b128 v[198:201], v209 offset:6144
	ds_read_b128 v[202:205], v209 offset:7168
	s_add_i32 s78, s78, 1
	s_mul_i32 s2, s78, s89
	s_mul_hi_u32 s3, s78, s53
	s_add_i32 s3, s3, s2
	s_mul_i32 s2, s78, s53
	s_add_u32 s2, s2, s46
	s_addc_u32 s3, s3, s52
	v_mov_b64_e32 v[2:3], 0xc60
	v_cmp_lt_i64_e64 s[6:7], s[2:3], v[2:3]
	v_mov_b64_e32 v[2:3], 0xc5f
	v_cmp_gt_i64_e32 vcc, s[2:3], v[2:3]
	s_nop 3
	s_mov_b32 s101, s6
	s_cbranch_vccnz .LBB0_1772
	s_ashr_i32 s3, s2, 31
	s_lshr_b32 s3, s3, 29
	s_add_i32 s3, s2, s3
	s_ashr_i32 s9, s3, 3
	s_and_b32 s3, s3, -8
	s_sub_i32 s2, s2, s3
	s_cmp_lt_i32 s2, 0
	s_movk_i32 s3, 0x18d
	s_cselect_b32 s3, s3, 0x18c
	s_mul_i32 s2, s2, s3
	s_add_i32 s2, s2, s9
	s_mul_hi_i32 s3, s2, 0x2e8ba2e9
	s_lshr_b32 s9, s3, 31
	s_ashr_i32 s3, s3, 6
	s_add_i32 s3, s3, s9
	s_lshl_b32 s9, s3, 3
	s_sub_i32 s11, 0x48, s9
	s_min_i32 s11, s11, 8
	s_abs_i32 s22, s11
	v_cvt_f32_u32_e32 v0, s22
	s_sub_i32 s36, 0, s22
	s_mulk_i32 s3, 0x160
	s_sub_i32 s2, s2, s3
	v_rcp_iflag_f32_e32 v0, v0
	s_abs_i32 s3, s2
	s_xor_b32 s23, s2, s11
	s_ashr_i32 s23, s23, 31
	v_mul_f32_e32 v0, 0x4f7ffffe, v0
	v_cvt_u32_f32_e32 v0, v0
	s_nop 0
	v_readfirstlane_b32 s37, v0
	s_mul_i32 s36, s36, s37
	s_mul_hi_u32 s36, s37, s36
	s_add_i32 s37, s37, s36
	s_mul_hi_u32 s36, s3, s37
	s_mul_i32 s37, s36, s22
	s_sub_i32 s3, s3, s37
	s_add_i32 s40, s36, 1
	s_sub_i32 s37, s3, s22
	s_cmp_ge_u32 s3, s22
	s_cselect_b32 s36, s40, s36
	s_cselect_b32 s3, s37, s3
	s_add_i32 s37, s36, 1
	s_cmp_ge_u32 s3, s22
	s_cselect_b32 s3, s37, s36
	s_xor_b32 s3, s3, s23
	s_sub_i32 s36, s3, s23
	s_mul_i32 s3, s36, s11
	s_sub_i32 s2, s2, s3
	s_add_i32 s40, s9, s2

;     __device__ __forceinline__ size_t aoff(const Unit& u) const { return (size_t)u.pm * bm * lda * 2; }
;     __device__ __forceinline__ size_t boff(const Unit& u) const { return (size_t)u.pn * BM * ldb * 2; }
;     __device__ __forceinline__ size_t aoff(const Unit& u) const { return ((size_t)u.pm * BM * lda + (size_t)u.pn * akoff) * 2; }
;     __device__ __forceinline__ size_t boff(const Unit& u) const { return (size_t)u.pn * BM * ldb * 2; }
;     __device__ __forceinline__ size_t aoff(const Unit& u) const { return ((size_t)u.pm * BM * lda + (size_t)(u.pn >> 1) * akoff) * 2; }
;     __device__ __forceinline__ size_t boff(const Unit& u) const { return (size_t)u.pn * BM * ldb * 2; }
; #define PG8_STAGE(bufoff, gbase, voff) do { _Pragma("unroll") for (int _i = 0; _i < 2; ++_i) \
;         __builtin_amdgcn_global_load_lds((const unsigned*)((const char*)(gbase) + (voff)[_i]), (LAS unsigned*)(lds + (bufoff) + ldsw + _i * 8192), 16, 0, 0); } while (0)
; #define PG8_LDA(dst, b, h) do { _Pragma("unroll") for (int m = 0; m < NM; ++m) _Pragma("unroll") for (int k = 0; k < 2; ++k) dst[m][k] = *(const LAS bf16x8*)(lds + PG8_SA(b, h) + aoff + m * 2048 + k * 1024); } while (0)
; #define PG8_BAR __builtin_amdgcn_s_barrier()
;     ...
;         const bool has_next = S.next(ui + 1, nxt);
;         const char* nA = has_next ? (const char*)g.A + S.aoff(nxt) : cA; const char* nB = has_next ? (const char*)g.Bt + S.boff(nxt) : cB;
;         if constexpr (Epi::PRE) E.pre(lds, cur, wid);
;         for (int t = 0; t < nt; t += 2) {
;             const bool last = (t == nt - 2);
;             const char* a1 = cA + (size_t)(t + 1) * kstep;
;             const char* a2 = last ? nA : cA + (size_t)(t + 2) * kstep; const char* b2 = last ? nB : cB + (size_t)(t + 2) * kstep;
;             const char* a3 = a2 + kstep; const char* b3 = b2 + kstep;
;             if constexpr (SP2) {
;             PG8_LDB(B0, 0, 0); PG8_LDB(B1, 0, 1); PG8_SCHED; PG8_LDA(At, 0, 0); PG8_STAGE(PG8_SA(1, 1), a1 + hstepA, voffA);
;             PG8_WAIT_V(8); PG8_WAIT_L(0); PG8_BAR; PG8_MMA(0, 0, At, B0); PG8_MMA(0, 1, At, B1); PG8_BAR; PG8_SCHED;
;             PG8_LDA(At, 0, 1); PG8_STAGE(PG8_SB(0, 0), b2, voffB); PG8_STAGE(PG8_SB(0, 1), b2 + hstepB, voffB); PG8_STAGE(PG8_SA(0, 0), a2, voffA);
;             PG8_WAIT_V(8); PG8_WAIT_L(0); PG8_BAR; PG8_MMA(1, 0, At, B0); PG8_MMA(1, 1, At, B1); PG8_BAR; PG8_SCHED;
.LBB0_1782:
	s_ashr_i32 s41, s40, 31
	s_lshl_b64 s[2:3], s[40:41], 20
	s_add_u32 s42, s33, s2
	s_addc_u32 s43, s48, s3
	s_and_b64 s[2:3], s[6:7], exec
	s_cselect_b32 s2, s43, s13
	s_cselect_b32 s3, s42, s12
	s_ashr_i32 s37, s36, 31
	s_lshl_b64 s[44:45], s[36:37], 20
	s_add_u32 s44, s60, s44
	s_addc_u32 s45, s63, s45
	s_and_b64 s[46:47], s[6:7], exec
	s_cselect_b32 s9, s45, s15
	s_cselect_b32 s11, s44, s14
	s_add_u32 s12, s12, 0x80080
	s_addc_u32 s13, s13, 0
	s_add_u32 s37, s14, 0x100
	s_addc_u32 s41, s15, 0
	s_mov_b32 vcc_lo, -2
	s_waitcnt vmcnt(5)
	s_add_u32 s14, s12, 0xfff80080
	s_addc_u32 s15, s13, -1
	s_cmp_eq_u32 vcc_lo, 28
	s_cselect_b32 s47, s2, s15
	s_cselect_b32 s46, s3, s14
	s_cselect_b32 s15, s9, s41
	s_cselect_b32 s14, s11, s37
	s_cselect_b32 s100, -1, 0
	s_andn2_b32 s100, s100, s101
	s_add_i32 m0, s73, 0xc000
	global_load_lds_dwordx4 v186, s[12:13]
	s_add_i32 m0, s73, 0xe000
	s_nop 0
	global_load_lds_dwordx4 v188, s[12:13]
	s_waitcnt vmcnt(8)
	s_waitcnt lgkmcnt(0)
	s_setprio 1
	s_barrier
	v_mfma_f32_16x16x32_bf16 v[126:129], v[130:133], v[162:165], 0
	v_mfma_f32_16x16x32_bf16 v[94:97], v[138:141], v[162:165], 0
	v_mfma_f32_16x16x32_bf16 v[110:113], v[130:133], v[170:173], 0
	v_mfma_f32_16x16x32_bf16 v[70:73], v[138:141], v[170:173], 0
	v_mfma_f32_16x16x32_bf16 v[106:109], v[130:133], v[190:193], 0
	v_mfma_f32_16x16x32_bf16 v[66:69], v[138:141], v[190:193], 0
	v_mfma_f32_16x16x32_bf16 v[118:121], v[130:133], v[198:201], 0
	v_mfma_f32_16x16x32_bf16 v[86:89], v[138:141], v[198:201], 0
	v_mfma_f32_16x16x32_bf16 v[126:129], v[134:137], v[166:169], v[126:129]
	v_mfma_f32_16x16x32_bf16 v[94:97], v[142:145], v[166:169], v[94:97]
	v_mfma_f32_16x16x32_bf16 v[110:113], v[134:137], v[174:177], v[110:113]
	v_mfma_f32_16x16x32_bf16 v[70:73], v[142:145], v[174:177], v[70:73]
	v_mfma_f32_16x16x32_bf16 v[106:109], v[134:137], v[194:197], v[106:109]
	v_mfma_f32_16x16x32_bf16 v[66:69], v[142:145], v[194:197], v[66:69]
	v_mfma_f32_16x16x32_bf16 v[118:121], v[134:137], v[202:205], v[118:121]
	v_mfma_f32_16x16x32_bf16 v[86:89], v[142:145], v[202:205], v[86:89]
	s_setprio 0
	s_setprio 1
	v_mfma_f32_16x16x32_bf16 v[122:125], v[146:149], v[162:165], 0
	v_mfma_f32_16x16x32_bf16 v[90:93], v[154:157], v[162:165], 0
	v_mfma_f32_16x16x32_bf16 v[102:105], v[146:149], v[170:173], 0
	v_mfma_f32_16x16x32_bf16 v[62:65], v[154:157], v[170:173], 0
	v_mfma_f32_16x16x32_bf16 v[98:101], v[146:149], v[190:193], 0
	v_mfma_f32_16x16x32_bf16 v[58:61], v[154:157], v[190:193], 0
	v_mfma_f32_16x16x32_bf16 v[114:117], v[146:149], v[198:201], 0
	v_mfma_f32_16x16x32_bf16 v[82:85], v[154:157], v[198:201], 0
	v_mfma_f32_16x16x32_bf16 v[122:125], v[150:153], v[166:169], v[122:125]
	v_mfma_f32_16x16x32_bf16 v[90:93], v[158:161], v[166:169], v[90:93]
	v_mfma_f32_16x16x32_bf16 v[102:105], v[150:153], v[174:177], v[102:105]
	v_mfma_f32_16x16x32_bf16 v[62:65], v[158:161], v[174:177], v[62:65]
	v_mfma_f32_16x16x32_bf16 v[98:101], v[150:153], v[194:197], v[98:101]
	v_mfma_f32_16x16x32_bf16 v[58:61], v[158:161], v[194:197], v[58:61]
	v_mfma_f32_16x16x32_bf16 v[114:117], v[150:153], v[202:205], v[114:117]
	v_mfma_f32_16x16x32_bf16 v[82:85], v[158:161], v[202:205], v[82:85]
	s_barrier
	s_setprio 0
	s_mov_b32 m0, s68
	s_add_u32 s22, s14, 0x80000
	s_addc_u32 s23, s15, 0
	ds_read_b128 v[162:165], v209 offset:16384
	ds_read_b128 v[166:169], v209 offset:17408
	ds_read_b128 v[170:173], v209 offset:18432
	ds_read_b128 v[174:177], v209 offset:19456
	ds_read_b128 v[190:193], v209 offset:20480
	ds_read_b128 v[194:197], v209 offset:21504
	ds_read_b128 v[198:201], v209 offset:22528
	ds_read_b128 v[202:205], v209 offset:23552
	s_cmp_lg_u32 s100, 0
	s_cbranch_scc1 .Ltl_up_0s_p
	global_load_lds_dwordx4 v180, s[14:15]
	s_mov_b32 m0, s69
	s_nop 0
	global_load_lds_dwordx4 v184, s[14:15]
	s_mov_b32 m0, s71
	s_nop 0
	global_load_lds_dwordx4 v180, s[22:23]
	s_mov_b32 m0, s72
	s_nop 0
	global_load_lds_dwordx4 v184, s[22:23]
	s_mov_b32 m0, s73
	s_nop 0
	global_load_lds_dwordx4 v178, s[46:47]
	s_mov_b32 m0, s74
	s_nop 0
	global_load_lds_dwordx4 v182, s[46:47]
	s_waitcnt vmcnt(8)
	s_branch .Ltl_up_0d_p

;     __device__ __forceinline__ size_t aoff(const Unit& u) const { return (size_t)u.pm * bm * lda * 2; }
;     __device__ __forceinline__ size_t boff(const Unit& u) const { return (size_t)u.pn * BM * ldb * 2; }
;     __device__ __forceinline__ size_t aoff(const Unit& u) const { return ((size_t)u.pm * BM * lda + (size_t)u.pn * akoff) * 2; }
;     __device__ __forceinline__ size_t boff(const Unit& u) const { return (size_t)u.pn * BM * ldb * 2; }
;     __device__ __forceinline__ size_t aoff(const Unit& u) const { return ((size_t)u.pm * BM * lda + (size_t)(u.pn >> 1) * akoff) * 2; }
;     __device__ __forceinline__ size_t boff(const Unit& u) const { return (size_t)u.pn * BM * ldb * 2; }
; #define PG8_STAGE(bufoff, gbase, voff) do { _Pragma("unroll") for (int _i = 0; _i < 2; ++_i) \
;         __builtin_amdgcn_global_load_lds((const unsigned*)((const char*)(gbase) + (voff)[_i]), (LAS unsigned*)(lds + (bufoff) + ldsw + _i * 8192), 16, 0, 0); } while (0)
; #define PG8_SCHED __builtin_amdgcn_sched_barrier(0)
;     __device__ bool next(int i, Unit& u) const {
;         const long L = (long)i * G + c; if (L >= nwg) return false;
;         int wgid = (int)L; { const int q = nwg / NXCD, r = nwg % NXCD, xcd = wgid % NXCD, off = wgid / NXCD; wgid = (xcd < r ? xcd * (q + 1) : r * (q + 1) + (xcd - r) * q) + off; }
;         const int nig = WGM * nN, gid = wgid / nig, fm = gid * WGM, gsz = (nM - fm) < WGM ? (nM - fm) : WGM;
;         u.pm = fm + ((wgid % nig) % gsz); u.pn = (wgid % nig) / gsz; return true;
;     }
;     ...
;         const bool has_next = S.next(ui + 1, nxt);
;         const char* nA = has_next ? (const char*)g.A + S.aoff(nxt) : cA; const char* nB = has_next ? (const char*)g.Bt + S.boff(nxt) : cB;
;         if constexpr (Epi::PRE) E.pre(lds, cur, wid);
;         for (int t = 0; t < nt; t += 2) {
;             const bool last = (t == nt - 2);
;             const char* a1 = cA + (size_t)(t + 1) * kstep;
;             const char* a2 = last ? nA : cA + (size_t)(t + 2) * kstep; const char* b2 = last ? nB : cB + (size_t)(t + 2) * kstep;
;             const char* a3 = a2 + kstep; const char* b3 = b2 + kstep;
;             if constexpr (SP2) {
;             PG8_LDB(B0, 0, 0); PG8_LDB(B1, 0, 1); PG8_SCHED; PG8_LDA(At, 0, 0); PG8_STAGE(PG8_SA(1, 1), a1 + hstepA, voffA);
.LBB0_2151:
	v_add_u32_e32 v102, s26, v166
	v_add_u32_e32 v126, s29, v166
	ds_read_b128 v[90:93], v102
	ds_read_b128 v[94:97], v102 offset:1024
	ds_read_b128 v[98:101], v102 offset:2048
	ds_read_b128 v[102:105], v102 offset:3072
	ds_read_b128 v[114:117], v126
	ds_read_b128 v[118:121], v126 offset:1024
	ds_read_b128 v[122:125], v126 offset:2048
	ds_read_b128 v[126:129], v126 offset:3072
	ds_read_b128 v[130:133], v167
	ds_read_b128 v[134:137], v167 offset:1024
	ds_read_b128 v[138:141], v167 offset:2048
	ds_read_b128 v[152:155], v167 offset:3072
	ds_read_b128 v[156:159], v167 offset:4096
	ds_read_b128 v[160:163], v167 offset:5120
	s_add_i32 s54, s54, 1
	s_mul_i32 s2, s54, s48
	s_mul_hi_u32 s3, s54, s53
	s_add_i32 s3, s3, s2
	s_mul_i32 s2, s54, s53
	v_readlane_b32 s4, v255, 29
	s_add_u32 s2, s2, s4
	s_addc_u32 s3, s3, s49
	v_mov_b64_e32 v[2:3], 0x300
	v_cmp_lt_i64_e64 s[6:7], s[2:3], v[2:3]
	v_mov_b64_e32 v[2:3], 0x2ff
	v_cmp_gt_i64_e32 vcc, s[2:3], v[2:3]
	s_nop 3
	s_mov_b32 s101, s6
	s_cbranch_vccnz .LBB0_2153
	s_ashr_i32 s3, s2, 31
	s_lshr_b32 s3, s3, 29
	s_add_i32 s3, s2, s3
	s_ashr_i32 s4, s3, 3
	s_and_b32 s3, s3, -8
	s_sub_i32 s2, s2, s3
	s_cmp_lt_i32 s2, 0
	s_movk_i32 s3, 0x61
	s_cselect_b32 s3, s3, 0x60
	s_mul_i32 s2, s2, s3
	s_add_i32 s2, s2, s4
	s_ashr_i32 s3, s2, 31
	s_lshr_b32 s3, s3, 26
	s_add_i32 s3, s2, s3
	s_ashr_i32 s4, s3, 6
	s_lshl_b32 s4, s4, 3
	s_sub_i32 s5, 0x60, s4
	s_min_i32 s5, s5, 8
	s_abs_i32 s12, s5
	v_cvt_f32_u32_e32 v2, s12
	s_sub_i32 s18, 0, s12
	s_andn2_b32 s3, s3, 63
	s_sub_i32 s2, s2, s3
	v_rcp_iflag_f32_e32 v2, v2
	s_abs_i32 s3, s2
	s_xor_b32 s13, s2, s5
	s_ashr_i32 s13, s13, 31
	v_mul_f32_e32 v2, 0x4f7ffffe, v2
	v_cvt_u32_f32_e32 v2, v2
	s_nop 0
	v_readfirstlane_b32 s19, v2
	s_mul_i32 s18, s18, s19
	s_mul_hi_u32 s18, s19, s18
	s_add_i32 s19, s19, s18
	s_mul_hi_u32 s18, s3, s19
	s_mul_i32 s19, s18, s12
	s_sub_i32 s3, s3, s19
	s_add_i32 s20, s18, 1
	s_sub_i32 s19, s3, s12
	s_cmp_ge_u32 s3, s12
	s_cselect_b32 s18, s20, s18
	s_cselect_b32 s3, s19, s3
	s_add_i32 s19, s18, 1
	s_cmp_ge_u32 s3, s12
	s_cselect_b32 s3, s19, s18
	s_xor_b32 s3, s3, s13
	s_sub_i32 s56, s3, s13
	s_mul_i32 s3, s56, s5
	s_sub_i32 s2, s2, s3
	s_add_i32 s57, s4, s2

;     __device__ __forceinline__ size_t aoff(const Unit& u) const { return (size_t)u.pm * bm * lda * 2; }
;     __device__ __forceinline__ size_t boff(const Unit& u) const { return (size_t)u.pn * BM * ldb * 2; }
;     __device__ __forceinline__ size_t aoff(const Unit& u) const { return ((size_t)u.pm * BM * lda + (size_t)u.pn * akoff) * 2; }
;     __device__ __forceinline__ size_t boff(const Unit& u) const { return (size_t)u.pn * BM * ldb * 2; }
;     __device__ __forceinline__ size_t aoff(const Unit& u) const { return ((size_t)u.pm * BM * lda + (size_t)(u.pn >> 1) * akoff) * 2; }
;     __device__ __forceinline__ size_t boff(const Unit& u) const { return (size_t)u.pn * BM * ldb * 2; }
; #define PG8_STAGE(bufoff, gbase, voff) do { _Pragma("unroll") for (int _i = 0; _i < 2; ++_i) \
;         __builtin_amdgcn_global_load_lds((const unsigned*)((const char*)(gbase) + (voff)[_i]), (LAS unsigned*)(lds + (bufoff) + ldsw + _i * 8192), 16, 0, 0); } while (0)
; #define PG8_LDA(dst, b, h) do { _Pragma("unroll") for (int m = 0; m < NM; ++m) _Pragma("unroll") for (int k = 0; k < 2; ++k) dst[m][k] = *(const LAS bf16x8*)(lds + PG8_SA(b, h) + aoff + m * 2048 + k * 1024); } while (0)
; #define PG8_LDB(dst, b, h) do { _Pragma("unroll") for (int n = 0; n < 2; ++n) _Pragma("unroll") for (int k = 0; k < 2; ++k) dst[n][k] = *(const LAS bf16x8*)(lds + PG8_SB(b, h) + boff + n * 2048 + k * 1024); } while (0)
; #define PG8_WAIT_V(n) asm volatile("s_waitcnt vmcnt(" #n ")" ::: "memory")
;     ...
;         const bool has_next = S.next(ui + 1, nxt);
;         const char* nA = has_next ? (const char*)g.A + S.aoff(nxt) : cA; const char* nB = has_next ? (const char*)g.Bt + S.boff(nxt) : cB;
;         if constexpr (Epi::PRE) E.pre(lds, cur, wid);
;         for (int t = 0; t < nt; t += 2) {
;             const bool last = (t == nt - 2);
;             const char* a1 = cA + (size_t)(t + 1) * kstep;
;             const char* a2 = last ? nA : cA + (size_t)(t + 2) * kstep; const char* b2 = last ? nB : cB + (size_t)(t + 2) * kstep;
;             const char* a3 = a2 + kstep; const char* b3 = b2 + kstep;
;             if constexpr (SP2) {
;             PG8_LDB(B0, 0, 0); PG8_LDB(B1, 0, 1); PG8_SCHED; PG8_LDA(At, 0, 0); PG8_STAGE(PG8_SA(1, 1), a1 + hstepA, voffA);
;             PG8_WAIT_V(8); PG8_WAIT_L(0); PG8_BAR; PG8_MMA(0, 0, At, B0); PG8_MMA(0, 1, At, B1); PG8_BAR; PG8_SCHED;
.LBB0_2157:
	s_add_u32 s2, s16, 0x100
	s_addc_u32 s3, s17, 0
	s_mov_b32 s60, -2
	s_waitcnt vmcnt(5)
	s_add_u32 s16, s14, 0x100
	s_addc_u32 s17, s15, 0
	s_cmpk_eq_i32 s60, 0x54
	s_cselect_b32 s21, s7, s17
	s_cselect_b32 s20, s6, s16
	s_cselect_b32 s19, s13, s3
	s_cselect_b32 s18, s12, s2
	s_cselect_b32 s100, -1, 0
	s_andn2_b32 s100, s100, s101
	s_add_i32 m0, s34, 0xc000
	global_load_lds_dwordx4 v148, s[14:15]
	s_add_i32 m0, s34, 0xe000
	s_nop 0
	s_and_b64 vcc, exec, s[8:9]
	s_cbranch_vccz .Lnm3d_skip0_p
	global_load_lds_dwordx4 v150, s[14:15]
	s_waitcnt vmcnt(8)
	s_branch .Lnm3d_done0_p
